# sc1
# baseline (speedup 1.0000x reference)
; #define LAS __attribute__((address_space(3)))
; __device__ __forceinline__ void transpose_tile(const float* src, int ldsrc, bf16_t* dst, int lddst, int k0, int n0, LAS unsigned char* lds) {
;     LAS unsigned short* T = (LAS unsigned short*)lds;
;     const int tid = threadIdx.x;
; #pragma unroll
;     for (int i = 0; i < 4; ++i) { const int idx = tid + i * NTHREADS, kr = idx >> 5, nq = idx & 31;
;         const f32x4 v = __builtin_nontemporal_load((const f32x4*)(src + (size_t)(k0 + kr) * ldsrc + n0 + nq * 4));
; #pragma unroll
;         for (int j = 0; j < 4; ++j) T[(nq * 4 + j) * 66 + kr] = f2bf(v[j]); }
;     __syncthreads();
; #pragma unroll
;     for (int i = 0; i < 2; ++i) { const int idx = tid + i * NTHREADS, n = idx >> 3, ch = idx & 7;
;         const LAS unsigned* rp = (const LAS unsigned*)(T + n * 66 + ch * 8);
;         u32x4 w; w.x = rp[0]; w.y = rp[1]; w.z = rp[2]; w.w = rp[3];
;         *(u32x4*)(dst + (size_t)(n0 + n) * lddst + k0 + ch * 8) = w; }
;     __syncthreads();
; }
; __device__ __forceinline__ void p0_prologue(const Params& p, LAS unsigned char* lds) {
;     ...
;     for (int t = blockIdx.x; t < 7808; t += G) {
;         if (t < 5120) { const int nt = t >> 6, kt = t & 63; const int n0 = (nt < 64 ? nt : nt + 16) * 128;
;             transpose_tile(p.w_in, NIN, win_t, DM, kt * 64, n0, lds); }
;         else if (t < 7168) { const int u = t - 5120, nt = u >> 6, kt = u & 63; transpose_tile(p.w_out, DM, wout_t, DM, kt * 64, nt * 128, lds); }
;         else if (t < 7296) { const int u = t - 7168, g = u >> 5, r = u & 31, nt = r >> 3, kt = r & 7;
;             transpose_tile(p.w_pool + (size_t)g * 512 * 512, 512, wpool_t + (size_t)g * 512 * 512, 512, kt * 64, nt * 128, lds); }
;         else { const int u = t - 7296; const int tid = threadIdx.x;
; #pragma unroll
;             for (int i = 0; i < 4; ++i) { const int row = u * 8 + (tid >> 8) + 2 * i, ch = tid & 255;
;                 const float* sp = p.w_in + (size_t)row * NIN + OFF_U + ch * 8;
;                 const f32x4 v0 = __builtin_nontemporal_load((const f32x4*)sp), v1 = __builtin_nontemporal_load((const f32x4*)(sp + 4));
;                 u32x4 w; w.x = cvt_pk_bf16(v0[0], v0[1]); w.y = cvt_pk_bf16(v0[2], v0[3]); w.z = cvt_pk_bf16(v1[0], v1[1]); w.w = cvt_pk_bf16(v1[2], v1[3]);
;                 *(u32x4*)(winu + (size_t)row * 2048 + ch * 8) = w; } }
.LBB0_19:
	s_cmpk_gt_i32 s36, 0x13ff
	s_mov_b64 s[8:9], -1
	s_cbranch_scc0 .LBB0_29
	s_cmpk_gt_u32 s36, 0x1bff
	s_cbranch_scc0 .LBB0_26
	s_cmpk_gt_u32 s36, 0x1c7f
	s_cbranch_scc0 .LBB0_23
	v_mov_b64_e32 v[42:43], s[26:27]
	v_mad_u64_u32 v[34:35], s[8:9], v14, s23, v[42:43]
	v_mov_b32_e32 v17, v3
	v_lshl_add_u64 v[38:39], v[34:35], 0, v[16:17]
	v_add_u32_e32 v2, 2, v14
	v_add_co_u32_e32 v34, vcc, 0x8000, v38
	v_mov_b32_e32 v15, v3
	v_mad_u64_u32 v[46:47], s[8:9], v2, s23, v[42:43]
	v_addc_co_u32_e32 v35, vcc, 0, v39, vcc
	v_lshlrev_b64 v[44:45], 12, v[14:15]
	v_lshl_add_u64 v[46:47], v[46:47], 0, v[16:17]
	global_load_dwordx4 v[34:37], v[34:35], off nt
	v_lshl_add_u64 v[38:39], v[38:39], 0, s[6:7]
	v_lshl_add_u64 v[44:45], v[4:5], 0, v[44:45]
	v_add_co_u32_e32 v48, vcc, s24, v46
	global_load_dwordx4 v[38:41], v[38:39], off offset:16 nt
	s_nop 0
	v_addc_co_u32_e32 v49, vcc, 0, v47, vcc
	s_waitcnt vmcnt(1)
	v_cvt_pk_bf16_f32 v34, v34, v35
	v_cvt_pk_bf16_f32 v35, v36, v37
	s_waitcnt vmcnt(0)
	v_cvt_pk_bf16_f32 v36, v38, v39
	v_cvt_pk_bf16_f32 v37, v40, v41
	global_store_dwordx4 v[44:45], v[34:37], off sc1
	v_lshlrev_b64 v[44:45], 12, v[2:3]
	v_add_u32_e32 v2, 4, v14
	global_load_dwordx4 v[34:37], v[48:49], off nt
	v_lshl_add_u64 v[38:39], v[46:47], 0, s[6:7]
	v_lshl_add_u64 v[44:45], v[4:5], 0, v[44:45]
	v_mad_u64_u32 v[46:47], s[8:9], v2, s23, v[42:43]
	global_load_dwordx4 v[38:41], v[38:39], off offset:16 nt
	v_lshl_add_u64 v[46:47], v[46:47], 0, v[16:17]
	s_waitcnt vmcnt(1)
	v_cvt_pk_bf16_f32 v34, v34, v35
	v_cvt_pk_bf16_f32 v35, v36, v37
	s_waitcnt vmcnt(0)
	v_cvt_pk_bf16_f32 v36, v38, v39
	v_cvt_pk_bf16_f32 v37, v40, v41
	global_store_dwordx4 v[44:45], v[34:37], off sc1
	v_lshlrev_b64 v[44:45], 12, v[2:3]
	v_add_u32_e32 v2, 6, v14
	v_add_co_u32_e32 v48, vcc, s24, v46
	v_mad_u64_u32 v[42:43], s[8:9], v2, s23, v[42:43]
	s_nop 0
	v_addc_co_u32_e32 v49, vcc, 0, v47, vcc
	v_lshl_add_u64 v[38:39], v[46:47], 0, s[6:7]
	v_lshl_add_u64 v[42:43], v[42:43], 0, v[16:17]
	global_load_dwordx4 v[34:37], v[48:49], off nt
	v_lshl_add_u64 v[44:45], v[4:5], 0, v[44:45]
	global_load_dwordx4 v[38:41], v[38:39], off offset:16 nt
	v_add_co_u32_e32 v46, vcc, s24, v42
	s_waitcnt vmcnt(1)
	v_cvt_pk_bf16_f32 v34, v34, v35
	v_cvt_pk_bf16_f32 v35, v36, v37
	s_waitcnt vmcnt(0)
	v_cvt_pk_bf16_f32 v36, v38, v39
	v_cvt_pk_bf16_f32 v37, v40, v41
	v_addc_co_u32_e32 v47, vcc, 0, v43, vcc
	global_store_dwordx4 v[44:45], v[34:37], off sc1
	v_lshl_add_u64 v[38:39], v[42:43], 0, s[6:7]
	v_lshlrev_b64 v[42:43], 12, v[2:3]
	global_load_dwordx4 v[34:37], v[46:47], off nt
	v_lshl_add_u64 v[42:43], v[4:5], 0, v[42:43]
	global_load_dwordx4 v[38:41], v[38:39], off offset:16 nt
	s_waitcnt vmcnt(1)
	v_cvt_pk_bf16_f32 v34, v34, v35
	v_cvt_pk_bf16_f32 v35, v36, v37
	s_waitcnt vmcnt(0)
	v_cvt_pk_bf16_f32 v36, v38, v39
	v_cvt_pk_bf16_f32 v37, v40, v41
	global_store_dwordx4 v[42:43], v[34:37], off sc1
	s_mov_b64 s[8:9], 0
.LBB0_23:
	s_andn2_b64 vcc, exec, s[8:9]
	s_cbranch_vccnz .LBB0_25
	s_add_i32 s0, s36, 0xffffe400
	s_lshr_b32 s0, s0, 5
	s_lshl_b64 s[8:9], s[0:1], 20
	s_add_u32 s37, s28, s8
	s_addc_u32 s46, s29, s9
	s_lshl_b64 s[8:9], s[0:1], 19
	s_add_u32 s0, s64, s8
	s_addc_u32 s47, s65, s9
	s_and_b32 s49, s13, 0x180
	s_and_b32 s48, s11, 0x1c0
	s_lshl_b32 s8, s49, 2
	s_add_u32 s8, s37, s8
	s_addc_u32 s9, s46, 0
	v_mov_b32_e32 v19, v3
	v_or_b32_e32 v2, s48, v23
	v_lshl_add_u64 v[46:47], s[8:9], 0, v[18:19]
	v_lshlrev_b32_e32 v2, 11, v2
	v_lshl_add_u64 v[34:35], v[46:47], 0, v[2:3]
	v_or_b32_e32 v2, s48, v25
	v_lshlrev_b32_e32 v2, 11, v2
	v_lshl_add_u64 v[38:39], v[46:47], 0, v[2:3]
	v_or_b32_e32 v2, s48, v27
	global_load_dwordx4 v[34:37], v[34:35], off nt
	v_lshlrev_b32_e32 v2, 11, v2
	global_load_dwordx4 v[38:41], v[38:39], off nt
	v_lshl_add_u64 v[42:43], v[46:47], 0, v[2:3]
	v_add_lshl_u32 v2, s48, v28, 11
	global_load_dwordx4 v[42:45], v[42:43], off nt
	v_lshl_add_u64 v[46:47], v[46:47], 0, v[2:3]
	global_load_dwordx4 v[46:49], v[46:47], off nt
	s_lshl_b32 s8, s48, 1
	s_add_u32 s8, s0, s8
	v_mov_b32_e32 v21, v3
	s_addc_u32 s9, s47, 0
	v_lshl_add_u64 v[50:51], s[8:9], 0, v[20:21]
	v_add_u32_e32 v15, v1, v24
	v_add_u32_e32 v17, v26, v24
	v_add_u32_e32 v19, v29, v24
	v_add_u32_e32 v52, v30, v31
	v_add_u32_e32 v53, v30, v33
	v_or_b32_e32 v2, s49, v133
	v_lshlrev_b32_e32 v2, 10, v2
	s_waitcnt vmcnt(3)
	v_bfe_u32 v21, v34, 16, 1
	v_bfe_u32 v54, v35, 16, 1
	v_bfe_u32 v55, v36, 16, 1
	v_bfe_u32 v56, v37, 16, 1
	v_add3_u32 v21, v34, v21, s25
	v_add3_u32 v34, v35, v54, s25
	v_add3_u32 v35, v36, v55, s25
	v_add3_u32 v36, v37, v56, s25
	s_waitcnt vmcnt(2)
	v_bfe_u32 v37, v38, 16, 1
	v_bfe_u32 v54, v39, 16, 1
	v_bfe_u32 v56, v41, 16, 1
	v_bfe_u32 v55, v40, 16, 1
	ds_write_b16_d16_hi v15, v21
	ds_write_b16_d16_hi v15, v34 offset:132
	ds_write_b16_d16_hi v15, v35 offset:264
	ds_write_b16_d16_hi v15, v36 offset:396
	v_add3_u32 v21, v38, v37, s25
	v_add3_u32 v34, v39, v54, s25
	v_add3_u32 v36, v41, v56, s25
	s_waitcnt vmcnt(1)
	v_bfe_u32 v37, v42, 16, 1
	v_bfe_u32 v39, v44, 16, 1
	v_add3_u32 v35, v40, v55, s25
	v_bfe_u32 v38, v43, 16, 1
	v_bfe_u32 v40, v45, 16, 1
	ds_write_b16_d16_hi v17, v21
	ds_write_b16_d16_hi v17, v34 offset:132
	ds_write_b16_d16_hi v17, v35 offset:264
	ds_write_b16_d16_hi v17, v36 offset:396
	v_add3_u32 v17, v42, v37, s25
	v_add3_u32 v34, v44, v39, s25
	s_waitcnt vmcnt(0)
	v_bfe_u32 v36, v46, 16, 1
	v_bfe_u32 v39, v49, 16, 1
	v_add3_u32 v21, v43, v38, s25
	v_add3_u32 v35, v45, v40, s25
	v_bfe_u32 v37, v47, 16, 1
	v_bfe_u32 v38, v48, 16, 1
	ds_write_b16_d16_hi v15, v17 offset:64
	ds_write_b16_d16_hi v15, v21 offset:196
	ds_write_b16_d16_hi v15, v34 offset:328
	ds_write_b16_d16_hi v15, v35 offset:460
	v_add3_u32 v15, v46, v36, s25
	v_add3_u32 v34, v49, v39, s25
	v_add3_u32 v17, v47, v37, s25
	v_add3_u32 v21, v48, v38, s25
	ds_write_b16_d16_hi v19, v15
	ds_write_b16_d16_hi v19, v17 offset:132
	ds_write_b16_d16_hi v19, v21 offset:264
	ds_write_b16_d16_hi v19, v34 offset:396
	s_waitcnt lgkmcnt(0)
	s_barrier
	ds_read2_b32 v[34:35], v52 offset1:1
	ds_read2_b32 v[36:37], v52 offset0:2 offset1:3
	ds_read2_b32 v[38:39], v53 offset1:1
	ds_read2_b32 v[40:41], v53 offset0:2 offset1:3
	v_lshl_add_u64 v[42:43], v[50:51], 0, v[2:3]
	v_add_lshl_u32 v2, s49, v32, 10
	v_lshl_add_u64 v[44:45], v[50:51], 0, v[2:3]
	s_waitcnt lgkmcnt(2)
	global_store_dwordx4 v[42:43], v[34:37], off sc1
	s_waitcnt lgkmcnt(0)
	global_store_dwordx4 v[44:45], v[38:41], off sc1
	s_barrier

; #define LAS __attribute__((address_space(3)))
; __device__ __forceinline__ unsigned short f2bf(float f) { unsigned u = __float_as_uint(f); u += 0x7fffu + ((u >> 16) & 1u); return (unsigned short)(u >> 16); }
; __device__ __forceinline__ void transpose_tile(const float* src, int ldsrc, bf16_t* dst, int lddst, int k0, int n0, LAS unsigned char* lds) {
;     LAS unsigned short* T = (LAS unsigned short*)lds;
;     const int tid = threadIdx.x;
; #pragma unroll
;     for (int i = 0; i < 4; ++i) { const int idx = tid + i * NTHREADS, kr = idx >> 5, nq = idx & 31;
;         const f32x4 v = __builtin_nontemporal_load((const f32x4*)(src + (size_t)(k0 + kr) * ldsrc + n0 + nq * 4));
; #pragma unroll
;         for (int j = 0; j < 4; ++j) T[(nq * 4 + j) * 66 + kr] = f2bf(v[j]); }
;     __syncthreads();
; #pragma unroll
;     for (int i = 0; i < 2; ++i) { const int idx = tid + i * NTHREADS, n = idx >> 3, ch = idx & 7;
;         const LAS unsigned* rp = (const LAS unsigned*)(T + n * 66 + ch * 8);
;         u32x4 w; w.x = rp[0]; w.y = rp[1]; w.z = rp[2]; w.w = rp[3];
;         *(u32x4*)(dst + (size_t)(n0 + n) * lddst + k0 + ch * 8) = w; }
;     __syncthreads();
; }
; __device__ __forceinline__ void p0_prologue(const Params& p, LAS unsigned char* lds) {
;     ...
;         else if (t < 7168) { const int u = t - 5120, nt = u >> 6, kt = u & 63; transpose_tile(p.w_out, DM, wout_t, DM, kt * 64, nt * 128, lds); }
.LBB0_26:
	s_andn2_b64 vcc, exec, s[8:9]
	s_cbranch_vccnz .LBB0_28
	s_and_b32 s8, s11, 0xfc0
	s_and_b32 s0, s19, 0x3f80
	s_addk_i32 s0, 0xd800
	v_or_b32_e32 v2, s8, v23
	v_lshl_add_u64 v[46:47], s[0:1], 2, v[10:11]
	v_lshlrev_b32_e32 v2, 14, v2
	v_lshl_add_u64 v[34:35], v[46:47], 0, v[2:3]
	v_or_b32_e32 v2, s8, v25
	v_lshlrev_b32_e32 v2, 14, v2
	v_lshl_add_u64 v[38:39], v[46:47], 0, v[2:3]
	v_or_b32_e32 v2, s8, v27
	global_load_dwordx4 v[34:37], v[34:35], off nt
	v_lshlrev_b32_e32 v2, 14, v2
	global_load_dwordx4 v[38:41], v[38:39], off nt
	v_lshl_add_u64 v[42:43], v[46:47], 0, v[2:3]
	v_add_lshl_u32 v2, s8, v28, 14
	global_load_dwordx4 v[42:45], v[42:43], off nt
	v_lshl_add_u64 v[46:47], v[46:47], 0, v[2:3]
	global_load_dwordx4 v[46:49], v[46:47], off nt
	v_add_u32_e32 v15, v1, v24
	v_add_u32_e32 v17, v26, v24
	v_add_u32_e32 v19, v29, v24
	v_add_u32_e32 v21, v30, v31
	v_add_u32_e32 v54, v30, v33
	s_mov_b32 s9, s1
	s_lshl_b32 s8, s8, 1
	v_or_b32_e32 v2, s0, v133
	v_lshl_add_u64 v[50:51], v[8:9], 0, s[8:9]
	v_lshlrev_b64 v[52:53], 13, v[2:3]
	v_add_u32_e32 v2, s0, v32
	s_waitcnt vmcnt(3)
	v_bfe_u32 v55, v34, 16, 1
	v_bfe_u32 v56, v35, 16, 1
	v_bfe_u32 v57, v36, 16, 1
	v_bfe_u32 v58, v37, 16, 1
	v_add3_u32 v34, v34, v55, s25
	v_add3_u32 v35, v35, v56, s25
	v_add3_u32 v36, v36, v57, s25
	v_add3_u32 v37, v37, v58, s25
	s_waitcnt vmcnt(2)
	v_bfe_u32 v55, v38, 16, 1
	v_bfe_u32 v56, v39, 16, 1
	v_bfe_u32 v57, v40, 16, 1
	v_bfe_u32 v58, v41, 16, 1
	ds_write_b16_d16_hi v15, v34
	ds_write_b16_d16_hi v15, v35 offset:132
	ds_write_b16_d16_hi v15, v36 offset:264
	ds_write_b16_d16_hi v15, v37 offset:396
	v_add3_u32 v34, v38, v55, s25
	v_add3_u32 v35, v39, v56, s25
	v_add3_u32 v36, v40, v57, s25
	v_add3_u32 v37, v41, v58, s25
	s_waitcnt vmcnt(1)
	v_bfe_u32 v38, v42, 16, 1
	v_bfe_u32 v39, v43, 16, 1
	v_bfe_u32 v40, v44, 16, 1
	v_bfe_u32 v41, v45, 16, 1
	ds_write_b16_d16_hi v17, v34
	ds_write_b16_d16_hi v17, v35 offset:132
	ds_write_b16_d16_hi v17, v36 offset:264
	ds_write_b16_d16_hi v17, v37 offset:396
	v_add3_u32 v17, v42, v38, s25
	v_add3_u32 v34, v43, v39, s25
	v_add3_u32 v35, v44, v40, s25
	s_waitcnt vmcnt(0)
	v_bfe_u32 v37, v46, 16, 1
	v_bfe_u32 v39, v48, 16, 1
	v_bfe_u32 v40, v49, 16, 1
	v_add3_u32 v36, v45, v41, s25
	v_bfe_u32 v38, v47, 16, 1
	ds_write_b16_d16_hi v15, v17 offset:64
	ds_write_b16_d16_hi v15, v34 offset:196
	ds_write_b16_d16_hi v15, v35 offset:328
	ds_write_b16_d16_hi v15, v36 offset:460
	v_add3_u32 v15, v46, v37, s25
	v_add3_u32 v34, v48, v39, s25
	v_add3_u32 v35, v49, v40, s25
	v_add3_u32 v17, v47, v38, s25
	ds_write_b16_d16_hi v19, v15
	ds_write_b16_d16_hi v19, v17 offset:132
	ds_write_b16_d16_hi v19, v34 offset:264
	ds_write_b16_d16_hi v19, v35 offset:396
	s_waitcnt lgkmcnt(0)
	s_barrier
	ds_read2_b32 v[34:35], v21 offset1:1
	ds_read2_b32 v[36:37], v21 offset0:2 offset1:3
	ds_read2_b32 v[38:39], v54 offset1:1
	ds_read2_b32 v[40:41], v54 offset0:2 offset1:3
	v_lshl_add_u64 v[42:43], v[50:51], 0, v[52:53]
	v_lshlrev_b64 v[44:45], 13, v[2:3]
	v_lshl_add_u64 v[44:45], v[50:51], 0, v[44:45]
	s_waitcnt lgkmcnt(2)
	global_store_dwordx4 v[42:43], v[34:37], off sc1
	s_waitcnt lgkmcnt(0)
	global_store_dwordx4 v[44:45], v[38:41], off sc1
	s_barrier

; #define LAS __attribute__((address_space(3)))
; __device__ __forceinline__ unsigned short f2bf(float f) { unsigned u = __float_as_uint(f); u += 0x7fffu + ((u >> 16) & 1u); return (unsigned short)(u >> 16); }
; __device__ __forceinline__ void transpose_tile(const float* src, int ldsrc, bf16_t* dst, int lddst, int k0, int n0, LAS unsigned char* lds) {
;     LAS unsigned short* T = (LAS unsigned short*)lds;
;     const int tid = threadIdx.x;
; #pragma unroll
;     for (int i = 0; i < 4; ++i) { const int idx = tid + i * NTHREADS, kr = idx >> 5, nq = idx & 31;
;         const f32x4 v = __builtin_nontemporal_load((const f32x4*)(src + (size_t)(k0 + kr) * ldsrc + n0 + nq * 4));
; #pragma unroll
;         for (int j = 0; j < 4; ++j) T[(nq * 4 + j) * 66 + kr] = f2bf(v[j]); }
;     __syncthreads();
; #pragma unroll
;     for (int i = 0; i < 2; ++i) { const int idx = tid + i * NTHREADS, n = idx >> 3, ch = idx & 7;
;         const LAS unsigned* rp = (const LAS unsigned*)(T + n * 66 + ch * 8);
;         u32x4 w; w.x = rp[0]; w.y = rp[1]; w.z = rp[2]; w.w = rp[3];
;         *(u32x4*)(dst + (size_t)(n0 + n) * lddst + k0 + ch * 8) = w; }
;     __syncthreads();
; }
; __device__ __forceinline__ void p0_prologue(const Params& p, LAS unsigned char* lds) {
;     ...
;         if (t < 5120) { const int nt = t >> 6, kt = t & 63; const int n0 = (nt < 64 ? nt : nt + 16) * 128;
;             transpose_tile(p.w_in, NIN, win_t, DM, kt * 64, n0, lds); }
.LBB0_29:
	s_andn2_b64 vcc, exec, s[8:9]
	s_cbranch_vccnz .LBB0_18
	s_ashr_i32 s0, s36, 6
	s_lshl_b32 s8, s0, 7
	s_add_i32 s9, s8, 0x800
	s_cmp_lt_i32 s0, 64
	s_cselect_b32 s8, s8, s9
	s_and_b32 s0, s11, 0xfc0
	v_or_b32_e32 v2, s0, v23
	s_ashr_i32 s9, s8, 31
	v_mul_u32_u24_e32 v2, 0x3000, v2
	v_lshl_add_u64 v[46:47], s[8:9], 2, v[12:13]
	v_lshlrev_b32_e32 v2, 2, v2
	v_lshl_add_u64 v[34:35], v[46:47], 0, v[2:3]
	v_or_b32_e32 v2, s0, v25
	v_mul_u32_u24_e32 v2, 0x3000, v2
	v_lshlrev_b32_e32 v2, 2, v2
	v_lshl_add_u64 v[38:39], v[46:47], 0, v[2:3]
	v_or_b32_e32 v2, s0, v27
	v_mul_u32_u24_e32 v2, 0x3000, v2
	v_lshlrev_b32_e32 v2, 2, v2
	v_lshl_add_u64 v[42:43], v[46:47], 0, v[2:3]
	v_add_u32_e32 v2, s0, v28
	global_load_dwordx4 v[34:37], v[34:35], off nt
	v_mul_u32_u24_e32 v2, 0x3000, v2
	global_load_dwordx4 v[38:41], v[38:39], off nt
	v_lshlrev_b32_e32 v2, 2, v2
	global_load_dwordx4 v[42:45], v[42:43], off nt
	v_lshl_add_u64 v[46:47], v[46:47], 0, v[2:3]
	global_load_dwordx4 v[46:49], v[46:47], off nt
	v_add_u32_e32 v2, v1, v24
	v_add_u32_e32 v15, v26, v24
	v_add_u32_e32 v17, v29, v24
	v_add_u32_e32 v19, v30, v31
	v_add_u32_e32 v21, v30, v33
	v_or_b32_e32 v50, s8, v133
	s_lshl_b32 s0, s0, 1
	v_add_u32_e32 v52, s8, v32
	v_ashrrev_i32_e32 v51, 31, v50
	v_lshl_add_u64 v[54:55], v[6:7], 0, s[0:1]
	v_ashrrev_i32_e32 v53, 31, v52
	v_lshlrev_b64 v[50:51], 13, v[50:51]
	s_waitcnt vmcnt(3)
	v_bfe_u32 v56, v34, 16, 1
	v_bfe_u32 v57, v35, 16, 1
	v_bfe_u32 v58, v36, 16, 1
	v_bfe_u32 v59, v37, 16, 1
	v_add3_u32 v34, v34, v56, s25
	v_add3_u32 v35, v35, v57, s25
	v_add3_u32 v36, v36, v58, s25
	v_add3_u32 v37, v37, v59, s25
	s_waitcnt vmcnt(2)
	v_bfe_u32 v56, v38, 16, 1
	v_bfe_u32 v57, v39, 16, 1
	v_bfe_u32 v58, v40, 16, 1
	v_bfe_u32 v59, v41, 16, 1
	ds_write_b16_d16_hi v2, v34
	ds_write_b16_d16_hi v2, v35 offset:132
	ds_write_b16_d16_hi v2, v36 offset:264
	ds_write_b16_d16_hi v2, v37 offset:396
	v_add3_u32 v34, v38, v56, s25
	v_add3_u32 v35, v39, v57, s25
	v_add3_u32 v36, v40, v58, s25
	v_add3_u32 v37, v41, v59, s25
	s_waitcnt vmcnt(1)
	v_bfe_u32 v38, v42, 16, 1
	v_bfe_u32 v39, v43, 16, 1
	v_bfe_u32 v40, v44, 16, 1
	v_bfe_u32 v41, v45, 16, 1
	ds_write_b16_d16_hi v15, v34
	ds_write_b16_d16_hi v15, v35 offset:132
	ds_write_b16_d16_hi v15, v36 offset:264
	ds_write_b16_d16_hi v15, v37 offset:396
	v_add3_u32 v15, v42, v38, s25
	v_add3_u32 v34, v43, v39, s25
	v_add3_u32 v35, v44, v40, s25
	s_waitcnt vmcnt(0)
	v_bfe_u32 v37, v46, 16, 1
	v_bfe_u32 v39, v48, 16, 1
	v_bfe_u32 v40, v49, 16, 1
	v_add3_u32 v36, v45, v41, s25
	v_bfe_u32 v38, v47, 16, 1
	ds_write_b16_d16_hi v2, v15 offset:64
	ds_write_b16_d16_hi v2, v34 offset:196
	ds_write_b16_d16_hi v2, v35 offset:328
	ds_write_b16_d16_hi v2, v36 offset:460
	v_add3_u32 v2, v46, v37, s25
	v_add3_u32 v34, v48, v39, s25
	v_add3_u32 v35, v49, v40, s25
	v_add3_u32 v15, v47, v38, s25
	ds_write_b16_d16_hi v17, v2
	ds_write_b16_d16_hi v17, v15 offset:132
	ds_write_b16_d16_hi v17, v34 offset:264
	ds_write_b16_d16_hi v17, v35 offset:396
	s_waitcnt lgkmcnt(0)
	s_barrier
	ds_read2_b32 v[34:35], v19 offset1:1
	ds_read2_b32 v[36:37], v19 offset0:2 offset1:3
	ds_read2_b32 v[38:39], v21 offset1:1
	ds_read2_b32 v[40:41], v21 offset0:2 offset1:3
	v_lshlrev_b64 v[42:43], 13, v[52:53]
	v_lshl_add_u64 v[44:45], v[54:55], 0, v[50:51]
	v_lshl_add_u64 v[42:43], v[54:55], 0, v[42:43]
	s_waitcnt lgkmcnt(2)
	global_store_dwordx4 v[44:45], v[34:37], off sc1
	s_waitcnt lgkmcnt(0)
	global_store_dwordx4 v[42:43], v[38:41], off sc1
	s_barrier
	s_branch .LBB0_18

; __device__ __forceinline__ unsigned cvt_pk_bf16(float lo, float hi) { unsigned r; asm volatile("v_cvt_pk_bf16_f32 %0, %1, %2" : "=v"(r) : "v"(lo), "v"(hi)); return r; }
; __device__ __forceinline__ float silu_f(float v) { return v * __builtin_amdgcn_rcpf(1.f + __expf(-v)); }
; __device__ __forceinline__ void unpack8(const u32x4 w, float (&f)[8]) { f[0] = bf_lo(w.x); f[1] = bf_hi(w.x); f[2] = bf_lo(w.y); f[3] = bf_hi(w.y); f[4] = bf_lo(w.z); f[5] = bf_hi(w.z); f[6] = bf_lo(w.w); f[7] = bf_hi(w.w); }
; __device__ __forceinline__ void p3_pool(const Params& p) {
;     ...
;         for (int tt = 0; tt < 32; ++tt) {
;             const int t = t0 + tt, pos = pos0 + tt;
;             float u[8], gp[8];
;             unpack8(*(const u32x4*)(proj + (size_t)t * NP2 + P2_U + j0), u);
;             unpack8(*(const u32x4*)(proj + (size_t)t * NP2 + P2_GP + j0), gp);
;             const float icnt = 1.f / (float)min(pos + 1, w);
;             float y[8];
; #pragma unroll
;             for (int j = 0; j < 8; ++j) { sum[j] += u[j]; y[j] = (sum[j] * icnt - u[j]) * ps[j] * silu_f(gp[j]); }
;             u32x4 o; o.x = cvt_pk_bf16(y[0], y[1]); o.y = cvt_pk_bf16(y[2], y[3]); o.z = cvt_pk_bf16(y[4], y[5]); o.w = cvt_pk_bf16(y[6], y[7]);
;             *(u32x4*)(ycat + (size_t)t * DM + 2048 + j0) = o;
;             if (pos - (w - 1) >= 0) { float f[8]; unpack8(*(const u32x4*)(proj + (size_t)(t - (w - 1)) * NP2 + P2_U + j0), f);
; #pragma unroll
;                 for (int j = 0; j < 8; ++j) sum[j] -= f[j]; }
.Lpq_join_1:
	v_lshlrev_b32_e32 v24, 16, v32
	v_and_b32_e32 v25, 0xffff0000, v32
	v_lshlrev_b32_e32 v26, 16, v36
	v_and_b32_e32 v27, 0xffff0000, v36
	v_add_f32_e32 v8, v8, v24
	v_add_f32_e32 v9, v9, v25
	v_mul_f32_e32 v28, 0xbfb8aa3b, v26
	v_mul_f32_e32 v29, 0xbfb8aa3b, v27
	v_exp_f32_e32 v28, v28
	v_exp_f32_e32 v29, v29
	v_fma_f32 v30, v18, v8, -v24
	v_fma_f32 v31, v18, v9, -v25
	v_add_f32_e32 v28, 1.0, v28
	v_add_f32_e32 v29, 1.0, v29
	v_rcp_f32_e32 v28, v28
	v_rcp_f32_e32 v29, v29
	v_mul_f32_e32 v30, v0, v30
	v_mul_f32_e32 v31, v1, v31
	v_mul_f32_e32 v28, v28, v26
	v_mul_f32_e32 v29, v29, v27
	v_mul_f32_e32 v30, v30, v28
	v_mul_f32_e32 v31, v31, v29
	v_cvt_pk_bf16_f32 v20, v30, v31
	v_lshlrev_b32_e32 v24, 16, v33
	v_and_b32_e32 v25, 0xffff0000, v33
	v_lshlrev_b32_e32 v26, 16, v37
	v_and_b32_e32 v27, 0xffff0000, v37
	v_add_f32_e32 v10, v10, v24
	v_add_f32_e32 v11, v11, v25
	v_mul_f32_e32 v28, 0xbfb8aa3b, v26
	v_mul_f32_e32 v29, 0xbfb8aa3b, v27
	v_exp_f32_e32 v28, v28
	v_exp_f32_e32 v29, v29
	v_fma_f32 v30, v18, v10, -v24
	v_fma_f32 v31, v18, v11, -v25
	v_add_f32_e32 v28, 1.0, v28
	v_add_f32_e32 v29, 1.0, v29
	v_rcp_f32_e32 v28, v28
	v_rcp_f32_e32 v29, v29
	v_mul_f32_e32 v30, v2, v30
	v_mul_f32_e32 v31, v3, v31
	v_mul_f32_e32 v28, v28, v26
	v_mul_f32_e32 v29, v29, v27
	v_mul_f32_e32 v30, v30, v28
	v_mul_f32_e32 v31, v31, v29
	v_cvt_pk_bf16_f32 v21, v30, v31
	v_lshlrev_b32_e32 v24, 16, v34
	v_and_b32_e32 v25, 0xffff0000, v34
	v_lshlrev_b32_e32 v26, 16, v38
	v_and_b32_e32 v27, 0xffff0000, v38
	v_add_f32_e32 v12, v12, v24
	v_add_f32_e32 v13, v13, v25
	v_mul_f32_e32 v28, 0xbfb8aa3b, v26
	v_mul_f32_e32 v29, 0xbfb8aa3b, v27
	v_exp_f32_e32 v28, v28
	v_exp_f32_e32 v29, v29
	v_fma_f32 v30, v18, v12, -v24
	v_fma_f32 v31, v18, v13, -v25
	v_add_f32_e32 v28, 1.0, v28
	v_add_f32_e32 v29, 1.0, v29
	v_rcp_f32_e32 v28, v28
	v_rcp_f32_e32 v29, v29
	v_mul_f32_e32 v30, v4, v30
	v_mul_f32_e32 v31, v5, v31
	v_mul_f32_e32 v28, v28, v26
	v_mul_f32_e32 v29, v29, v27
	v_mul_f32_e32 v30, v30, v28
	v_mul_f32_e32 v31, v31, v29
	v_cvt_pk_bf16_f32 v22, v30, v31
	v_lshlrev_b32_e32 v24, 16, v35
	v_and_b32_e32 v25, 0xffff0000, v35
	v_lshlrev_b32_e32 v26, 16, v39
	v_and_b32_e32 v27, 0xffff0000, v39
	v_add_f32_e32 v14, v14, v24
	v_add_f32_e32 v15, v15, v25
	v_mul_f32_e32 v28, 0xbfb8aa3b, v26
	v_mul_f32_e32 v29, 0xbfb8aa3b, v27
	v_exp_f32_e32 v28, v28
	v_exp_f32_e32 v29, v29
	v_fma_f32 v30, v18, v14, -v24
	v_fma_f32 v31, v18, v15, -v25
	v_add_f32_e32 v28, 1.0, v28
	v_add_f32_e32 v29, 1.0, v29
	v_rcp_f32_e32 v28, v28
	v_rcp_f32_e32 v29, v29
	v_mul_f32_e32 v30, v6, v30
	v_mul_f32_e32 v31, v7, v31
	v_mul_f32_e32 v28, v28, v26
	v_mul_f32_e32 v29, v29, v27
	v_mul_f32_e32 v30, v30, v28
	v_mul_f32_e32 v31, v31, v29
	v_cvt_pk_bf16_f32 v23, v30, v31
	global_store_dwordx4 v16, v[20:23], s[8:9] sc1
	s_add_u32 s8, s8, 0x2000
	s_addc_u32 s9, s9, 0
	s_cmp_lt_u32 s23, s11
	s_cbranch_scc1 .Lpq_nolag_1
	v_lshlrev_b32_e32 v24, 16, v40
	v_and_b32_e32 v25, 0xffff0000, v40
	v_sub_f32_e32 v8, v8, v24
	v_sub_f32_e32 v9, v9, v25
	v_lshlrev_b32_e32 v24, 16, v41
	v_and_b32_e32 v25, 0xffff0000, v41
	v_sub_f32_e32 v10, v10, v24
	v_sub_f32_e32 v11, v11, v25
	v_lshlrev_b32_e32 v24, 16, v42
	v_and_b32_e32 v25, 0xffff0000, v42
	v_sub_f32_e32 v12, v12, v24
	v_sub_f32_e32 v13, v13, v25
	v_lshlrev_b32_e32 v24, 16, v43
	v_and_b32_e32 v25, 0xffff0000, v43
	v_sub_f32_e32 v14, v14, v24
	v_sub_f32_e32 v15, v15, v25

; __device__ __forceinline__ unsigned cvt_pk_bf16(float lo, float hi) { unsigned r; asm volatile("v_cvt_pk_bf16_f32 %0, %1, %2" : "=v"(r) : "v"(lo), "v"(hi)); return r; }
; __device__ __forceinline__ float silu_f(float v) { return v * __builtin_amdgcn_rcpf(1.f + __expf(-v)); }
; __device__ __forceinline__ void unpack8(const u32x4 w, float (&f)[8]) { f[0] = bf_lo(w.x); f[1] = bf_hi(w.x); f[2] = bf_lo(w.y); f[3] = bf_hi(w.y); f[4] = bf_lo(w.z); f[5] = bf_hi(w.z); f[6] = bf_lo(w.w); f[7] = bf_hi(w.w); }
; __device__ __forceinline__ void p3_pool(const Params& p) {
;     ...
;         for (int tt = 0; tt < 32; ++tt) {
;             const int t = t0 + tt, pos = pos0 + tt;
;             float u[8], gp[8];
;             unpack8(*(const u32x4*)(proj + (size_t)t * NP2 + P2_U + j0), u);
;             unpack8(*(const u32x4*)(proj + (size_t)t * NP2 + P2_GP + j0), gp);
;             const float icnt = 1.f / (float)min(pos + 1, w);
;             float y[8];
; #pragma unroll
;             for (int j = 0; j < 8; ++j) { sum[j] += u[j]; y[j] = (sum[j] * icnt - u[j]) * ps[j] * silu_f(gp[j]); }
;             u32x4 o; o.x = cvt_pk_bf16(y[0], y[1]); o.y = cvt_pk_bf16(y[2], y[3]); o.z = cvt_pk_bf16(y[4], y[5]); o.w = cvt_pk_bf16(y[6], y[7]);
;             *(u32x4*)(ycat + (size_t)t * DM + 2048 + j0) = o;
;             if (pos - (w - 1) >= 0) { float f[8]; unpack8(*(const u32x4*)(proj + (size_t)(t - (w - 1)) * NP2 + P2_U + j0), f);
; #pragma unroll
;                 for (int j = 0; j < 8; ++j) sum[j] -= f[j]; }
.Lpq_join_2:
	v_lshlrev_b32_e32 v24, 16, v44
	v_and_b32_e32 v25, 0xffff0000, v44
	v_lshlrev_b32_e32 v26, 16, v48
	v_and_b32_e32 v27, 0xffff0000, v48
	v_add_f32_e32 v8, v8, v24
	v_add_f32_e32 v9, v9, v25
	v_mul_f32_e32 v28, 0xbfb8aa3b, v26
	v_mul_f32_e32 v29, 0xbfb8aa3b, v27
	v_exp_f32_e32 v28, v28
	v_exp_f32_e32 v29, v29
	v_fma_f32 v30, v18, v8, -v24
	v_fma_f32 v31, v18, v9, -v25
	v_add_f32_e32 v28, 1.0, v28
	v_add_f32_e32 v29, 1.0, v29
	v_rcp_f32_e32 v28, v28
	v_rcp_f32_e32 v29, v29
	v_mul_f32_e32 v30, v0, v30
	v_mul_f32_e32 v31, v1, v31
	v_mul_f32_e32 v28, v28, v26
	v_mul_f32_e32 v29, v29, v27
	v_mul_f32_e32 v30, v30, v28
	v_mul_f32_e32 v31, v31, v29
	v_cvt_pk_bf16_f32 v20, v30, v31
	v_lshlrev_b32_e32 v24, 16, v45
	v_and_b32_e32 v25, 0xffff0000, v45
	v_lshlrev_b32_e32 v26, 16, v49
	v_and_b32_e32 v27, 0xffff0000, v49
	v_add_f32_e32 v10, v10, v24
	v_add_f32_e32 v11, v11, v25
	v_mul_f32_e32 v28, 0xbfb8aa3b, v26
	v_mul_f32_e32 v29, 0xbfb8aa3b, v27
	v_exp_f32_e32 v28, v28
	v_exp_f32_e32 v29, v29
	v_fma_f32 v30, v18, v10, -v24
	v_fma_f32 v31, v18, v11, -v25
	v_add_f32_e32 v28, 1.0, v28
	v_add_f32_e32 v29, 1.0, v29
	v_rcp_f32_e32 v28, v28
	v_rcp_f32_e32 v29, v29
	v_mul_f32_e32 v30, v2, v30
	v_mul_f32_e32 v31, v3, v31
	v_mul_f32_e32 v28, v28, v26
	v_mul_f32_e32 v29, v29, v27
	v_mul_f32_e32 v30, v30, v28
	v_mul_f32_e32 v31, v31, v29
	v_cvt_pk_bf16_f32 v21, v30, v31
	v_lshlrev_b32_e32 v24, 16, v46
	v_and_b32_e32 v25, 0xffff0000, v46
	v_lshlrev_b32_e32 v26, 16, v50
	v_and_b32_e32 v27, 0xffff0000, v50
	v_add_f32_e32 v12, v12, v24
	v_add_f32_e32 v13, v13, v25
	v_mul_f32_e32 v28, 0xbfb8aa3b, v26
	v_mul_f32_e32 v29, 0xbfb8aa3b, v27
	v_exp_f32_e32 v28, v28
	v_exp_f32_e32 v29, v29
	v_fma_f32 v30, v18, v12, -v24
	v_fma_f32 v31, v18, v13, -v25
	v_add_f32_e32 v28, 1.0, v28
	v_add_f32_e32 v29, 1.0, v29
	v_rcp_f32_e32 v28, v28
	v_rcp_f32_e32 v29, v29
	v_mul_f32_e32 v30, v4, v30
	v_mul_f32_e32 v31, v5, v31
	v_mul_f32_e32 v28, v28, v26
	v_mul_f32_e32 v29, v29, v27
	v_mul_f32_e32 v30, v30, v28
	v_mul_f32_e32 v31, v31, v29
	v_cvt_pk_bf16_f32 v22, v30, v31
	v_lshlrev_b32_e32 v24, 16, v47
	v_and_b32_e32 v25, 0xffff0000, v47
	v_lshlrev_b32_e32 v26, 16, v51
	v_and_b32_e32 v27, 0xffff0000, v51
	v_add_f32_e32 v14, v14, v24
	v_add_f32_e32 v15, v15, v25
	v_mul_f32_e32 v28, 0xbfb8aa3b, v26
	v_mul_f32_e32 v29, 0xbfb8aa3b, v27
	v_exp_f32_e32 v28, v28
	v_exp_f32_e32 v29, v29
	v_fma_f32 v30, v18, v14, -v24
	v_fma_f32 v31, v18, v15, -v25
	v_add_f32_e32 v28, 1.0, v28
	v_add_f32_e32 v29, 1.0, v29
	v_rcp_f32_e32 v28, v28
	v_rcp_f32_e32 v29, v29
	v_mul_f32_e32 v30, v6, v30
	v_mul_f32_e32 v31, v7, v31
	v_mul_f32_e32 v28, v28, v26
	v_mul_f32_e32 v29, v29, v27
	v_mul_f32_e32 v30, v30, v28
	v_mul_f32_e32 v31, v31, v29
	v_cvt_pk_bf16_f32 v23, v30, v31
	global_store_dwordx4 v16, v[20:23], s[8:9] sc1
	s_add_u32 s8, s8, 0x2000
	s_addc_u32 s9, s9, 0
	s_cmp_lt_u32 s23, s11
	s_cbranch_scc1 .Lpq_nolag_2
	v_lshlrev_b32_e32 v24, 16, v52
	v_and_b32_e32 v25, 0xffff0000, v52
	v_sub_f32_e32 v8, v8, v24
	v_sub_f32_e32 v9, v9, v25
	v_lshlrev_b32_e32 v24, 16, v53
	v_and_b32_e32 v25, 0xffff0000, v53
	v_sub_f32_e32 v10, v10, v24
	v_sub_f32_e32 v11, v11, v25
	v_lshlrev_b32_e32 v24, 16, v54
	v_and_b32_e32 v25, 0xffff0000, v54
	v_sub_f32_e32 v12, v12, v24
	v_sub_f32_e32 v13, v13, v25
	v_lshlrev_b32_e32 v24, 16, v55
	v_and_b32_e32 v25, 0xffff0000, v55
	v_sub_f32_e32 v14, v14, v24
	v_sub_f32_e32 v15, v15, v25

; __device__ __forceinline__ unsigned cvt_pk_bf16(float lo, float hi) { unsigned r; asm volatile("v_cvt_pk_bf16_f32 %0, %1, %2" : "=v"(r) : "v"(lo), "v"(hi)); return r; }
; __device__ __forceinline__ float silu_f(float v) { return v * __builtin_amdgcn_rcpf(1.f + __expf(-v)); }
; __device__ __forceinline__ void unpack8(const u32x4 w, float (&f)[8]) { f[0] = bf_lo(w.x); f[1] = bf_hi(w.x); f[2] = bf_lo(w.y); f[3] = bf_hi(w.y); f[4] = bf_lo(w.z); f[5] = bf_hi(w.z); f[6] = bf_lo(w.w); f[7] = bf_hi(w.w); }
; __device__ __forceinline__ void p3_pool(const Params& p) {
;     ...
;         for (int tt = 0; tt < 32; ++tt) {
;             const int t = t0 + tt, pos = pos0 + tt;
;             float u[8], gp[8];
;             unpack8(*(const u32x4*)(proj + (size_t)t * NP2 + P2_U + j0), u);
;             unpack8(*(const u32x4*)(proj + (size_t)t * NP2 + P2_GP + j0), gp);
;             const float icnt = 1.f / (float)min(pos + 1, w);
;             float y[8];
; #pragma unroll
;             for (int j = 0; j < 8; ++j) { sum[j] += u[j]; y[j] = (sum[j] * icnt - u[j]) * ps[j] * silu_f(gp[j]); }
;             u32x4 o; o.x = cvt_pk_bf16(y[0], y[1]); o.y = cvt_pk_bf16(y[2], y[3]); o.z = cvt_pk_bf16(y[4], y[5]); o.w = cvt_pk_bf16(y[6], y[7]);
;             *(u32x4*)(ycat + (size_t)t * DM + 2048 + j0) = o;
;             if (pos - (w - 1) >= 0) { float f[8]; unpack8(*(const u32x4*)(proj + (size_t)(t - (w - 1)) * NP2 + P2_U + j0), f);
; #pragma unroll
;                 for (int j = 0; j < 8; ++j) sum[j] -= f[j]; }
.Lpq_join_3:
	v_lshlrev_b32_e32 v24, 16, v56
	v_and_b32_e32 v25, 0xffff0000, v56
	v_lshlrev_b32_e32 v26, 16, v60
	v_and_b32_e32 v27, 0xffff0000, v60
	v_add_f32_e32 v8, v8, v24
	v_add_f32_e32 v9, v9, v25
	v_mul_f32_e32 v28, 0xbfb8aa3b, v26
	v_mul_f32_e32 v29, 0xbfb8aa3b, v27
	v_exp_f32_e32 v28, v28
	v_exp_f32_e32 v29, v29
	v_fma_f32 v30, v18, v8, -v24
	v_fma_f32 v31, v18, v9, -v25
	v_add_f32_e32 v28, 1.0, v28
	v_add_f32_e32 v29, 1.0, v29
	v_rcp_f32_e32 v28, v28
	v_rcp_f32_e32 v29, v29
	v_mul_f32_e32 v30, v0, v30
	v_mul_f32_e32 v31, v1, v31
	v_mul_f32_e32 v28, v28, v26
	v_mul_f32_e32 v29, v29, v27
	v_mul_f32_e32 v30, v30, v28
	v_mul_f32_e32 v31, v31, v29
	v_cvt_pk_bf16_f32 v20, v30, v31
	v_lshlrev_b32_e32 v24, 16, v57
	v_and_b32_e32 v25, 0xffff0000, v57
	v_lshlrev_b32_e32 v26, 16, v61
	v_and_b32_e32 v27, 0xffff0000, v61
	v_add_f32_e32 v10, v10, v24
	v_add_f32_e32 v11, v11, v25
	v_mul_f32_e32 v28, 0xbfb8aa3b, v26
	v_mul_f32_e32 v29, 0xbfb8aa3b, v27
	v_exp_f32_e32 v28, v28
	v_exp_f32_e32 v29, v29
	v_fma_f32 v30, v18, v10, -v24
	v_fma_f32 v31, v18, v11, -v25
	v_add_f32_e32 v28, 1.0, v28
	v_add_f32_e32 v29, 1.0, v29
	v_rcp_f32_e32 v28, v28
	v_rcp_f32_e32 v29, v29
	v_mul_f32_e32 v30, v2, v30
	v_mul_f32_e32 v31, v3, v31
	v_mul_f32_e32 v28, v28, v26
	v_mul_f32_e32 v29, v29, v27
	v_mul_f32_e32 v30, v30, v28
	v_mul_f32_e32 v31, v31, v29
	v_cvt_pk_bf16_f32 v21, v30, v31
	v_lshlrev_b32_e32 v24, 16, v58
	v_and_b32_e32 v25, 0xffff0000, v58
	v_lshlrev_b32_e32 v26, 16, v62
	v_and_b32_e32 v27, 0xffff0000, v62
	v_add_f32_e32 v12, v12, v24
	v_add_f32_e32 v13, v13, v25
	v_mul_f32_e32 v28, 0xbfb8aa3b, v26
	v_mul_f32_e32 v29, 0xbfb8aa3b, v27
	v_exp_f32_e32 v28, v28
	v_exp_f32_e32 v29, v29
	v_fma_f32 v30, v18, v12, -v24
	v_fma_f32 v31, v18, v13, -v25
	v_add_f32_e32 v28, 1.0, v28
	v_add_f32_e32 v29, 1.0, v29
	v_rcp_f32_e32 v28, v28
	v_rcp_f32_e32 v29, v29
	v_mul_f32_e32 v30, v4, v30
	v_mul_f32_e32 v31, v5, v31
	v_mul_f32_e32 v28, v28, v26
	v_mul_f32_e32 v29, v29, v27
	v_mul_f32_e32 v30, v30, v28
	v_mul_f32_e32 v31, v31, v29
	v_cvt_pk_bf16_f32 v22, v30, v31
	v_lshlrev_b32_e32 v24, 16, v59
	v_and_b32_e32 v25, 0xffff0000, v59
	v_lshlrev_b32_e32 v26, 16, v63
	v_and_b32_e32 v27, 0xffff0000, v63
	v_add_f32_e32 v14, v14, v24
	v_add_f32_e32 v15, v15, v25
	v_mul_f32_e32 v28, 0xbfb8aa3b, v26
	v_mul_f32_e32 v29, 0xbfb8aa3b, v27
	v_exp_f32_e32 v28, v28
	v_exp_f32_e32 v29, v29
	v_fma_f32 v30, v18, v14, -v24
	v_fma_f32 v31, v18, v15, -v25
	v_add_f32_e32 v28, 1.0, v28
	v_add_f32_e32 v29, 1.0, v29
	v_rcp_f32_e32 v28, v28
	v_rcp_f32_e32 v29, v29
	v_mul_f32_e32 v30, v6, v30
	v_mul_f32_e32 v31, v7, v31
	v_mul_f32_e32 v28, v28, v26
	v_mul_f32_e32 v29, v29, v27
	v_mul_f32_e32 v30, v30, v28
	v_mul_f32_e32 v31, v31, v29
	v_cvt_pk_bf16_f32 v23, v30, v31
	global_store_dwordx4 v16, v[20:23], s[8:9] sc1
	s_add_u32 s8, s8, 0x2000
	s_addc_u32 s9, s9, 0
	s_cmp_lt_u32 s23, s11
	s_cbranch_scc1 .Lpq_nolag_3
	v_lshlrev_b32_e32 v24, 16, v64
	v_and_b32_e32 v25, 0xffff0000, v64
	v_sub_f32_e32 v8, v8, v24
	v_sub_f32_e32 v9, v9, v25
	v_lshlrev_b32_e32 v24, 16, v65
	v_and_b32_e32 v25, 0xffff0000, v65
	v_sub_f32_e32 v10, v10, v24
	v_sub_f32_e32 v11, v11, v25
	v_lshlrev_b32_e32 v24, 16, v66
	v_and_b32_e32 v25, 0xffff0000, v66
	v_sub_f32_e32 v12, v12, v24
	v_sub_f32_e32 v13, v13, v25
	v_lshlrev_b32_e32 v24, 16, v67
	v_and_b32_e32 v25, 0xffff0000, v67
	v_sub_f32_e32 v14, v14, v24
	v_sub_f32_e32 v15, v15, v25

; __device__ __forceinline__ unsigned cvt_pk_bf16(float lo, float hi) { unsigned r; asm volatile("v_cvt_pk_bf16_f32 %0, %1, %2" : "=v"(r) : "v"(lo), "v"(hi)); return r; }
; __device__ __forceinline__ float silu_f(float v) { return v * __builtin_amdgcn_rcpf(1.f + __expf(-v)); }
; __device__ __forceinline__ void unpack8(const u32x4 w, float (&f)[8]) { f[0] = bf_lo(w.x); f[1] = bf_hi(w.x); f[2] = bf_lo(w.y); f[3] = bf_hi(w.y); f[4] = bf_lo(w.z); f[5] = bf_hi(w.z); f[6] = bf_lo(w.w); f[7] = bf_hi(w.w); }
; __device__ __forceinline__ void p3_pool(const Params& p) {
;     ...
;         for (int tt = 0; tt < 32; ++tt) {
;             const int t = t0 + tt, pos = pos0 + tt;
;             float u[8], gp[8];
;             unpack8(*(const u32x4*)(proj + (size_t)t * NP2 + P2_U + j0), u);
;             unpack8(*(const u32x4*)(proj + (size_t)t * NP2 + P2_GP + j0), gp);
;             const float icnt = 1.f / (float)min(pos + 1, w);
;             float y[8];
; #pragma unroll
;             for (int j = 0; j < 8; ++j) { sum[j] += u[j]; y[j] = (sum[j] * icnt - u[j]) * ps[j] * silu_f(gp[j]); }
;             u32x4 o; o.x = cvt_pk_bf16(y[0], y[1]); o.y = cvt_pk_bf16(y[2], y[3]); o.z = cvt_pk_bf16(y[4], y[5]); o.w = cvt_pk_bf16(y[6], y[7]);
;             *(u32x4*)(ycat + (size_t)t * DM + 2048 + j0) = o;
;             if (pos - (w - 1) >= 0) { float f[8]; unpack8(*(const u32x4*)(proj + (size_t)(t - (w - 1)) * NP2 + P2_U + j0), f);
; #pragma unroll
;                 for (int j = 0; j < 8; ++j) sum[j] -= f[j]; }
.Lpq_join_4:
	v_lshlrev_b32_e32 v24, 16, v68
	v_and_b32_e32 v25, 0xffff0000, v68
	v_lshlrev_b32_e32 v26, 16, v72
	v_and_b32_e32 v27, 0xffff0000, v72
	v_add_f32_e32 v8, v8, v24
	v_add_f32_e32 v9, v9, v25
	v_mul_f32_e32 v28, 0xbfb8aa3b, v26
	v_mul_f32_e32 v29, 0xbfb8aa3b, v27
	v_exp_f32_e32 v28, v28
	v_exp_f32_e32 v29, v29
	v_fma_f32 v30, v18, v8, -v24
	v_fma_f32 v31, v18, v9, -v25
	v_add_f32_e32 v28, 1.0, v28
	v_add_f32_e32 v29, 1.0, v29
	v_rcp_f32_e32 v28, v28
	v_rcp_f32_e32 v29, v29
	v_mul_f32_e32 v30, v0, v30
	v_mul_f32_e32 v31, v1, v31
	v_mul_f32_e32 v28, v28, v26
	v_mul_f32_e32 v29, v29, v27
	v_mul_f32_e32 v30, v30, v28
	v_mul_f32_e32 v31, v31, v29
	v_cvt_pk_bf16_f32 v20, v30, v31
	v_lshlrev_b32_e32 v24, 16, v69
	v_and_b32_e32 v25, 0xffff0000, v69
	v_lshlrev_b32_e32 v26, 16, v73
	v_and_b32_e32 v27, 0xffff0000, v73
	v_add_f32_e32 v10, v10, v24
	v_add_f32_e32 v11, v11, v25
	v_mul_f32_e32 v28, 0xbfb8aa3b, v26
	v_mul_f32_e32 v29, 0xbfb8aa3b, v27
	v_exp_f32_e32 v28, v28
	v_exp_f32_e32 v29, v29
	v_fma_f32 v30, v18, v10, -v24
	v_fma_f32 v31, v18, v11, -v25
	v_add_f32_e32 v28, 1.0, v28
	v_add_f32_e32 v29, 1.0, v29
	v_rcp_f32_e32 v28, v28
	v_rcp_f32_e32 v29, v29
	v_mul_f32_e32 v30, v2, v30
	v_mul_f32_e32 v31, v3, v31
	v_mul_f32_e32 v28, v28, v26
	v_mul_f32_e32 v29, v29, v27
	v_mul_f32_e32 v30, v30, v28
	v_mul_f32_e32 v31, v31, v29
	v_cvt_pk_bf16_f32 v21, v30, v31
	v_lshlrev_b32_e32 v24, 16, v70
	v_and_b32_e32 v25, 0xffff0000, v70
	v_lshlrev_b32_e32 v26, 16, v74
	v_and_b32_e32 v27, 0xffff0000, v74
	v_add_f32_e32 v12, v12, v24
	v_add_f32_e32 v13, v13, v25
	v_mul_f32_e32 v28, 0xbfb8aa3b, v26
	v_mul_f32_e32 v29, 0xbfb8aa3b, v27
	v_exp_f32_e32 v28, v28
	v_exp_f32_e32 v29, v29
	v_fma_f32 v30, v18, v12, -v24
	v_fma_f32 v31, v18, v13, -v25
	v_add_f32_e32 v28, 1.0, v28
	v_add_f32_e32 v29, 1.0, v29
	v_rcp_f32_e32 v28, v28
	v_rcp_f32_e32 v29, v29
	v_mul_f32_e32 v30, v4, v30
	v_mul_f32_e32 v31, v5, v31
	v_mul_f32_e32 v28, v28, v26
	v_mul_f32_e32 v29, v29, v27
	v_mul_f32_e32 v30, v30, v28
	v_mul_f32_e32 v31, v31, v29
	v_cvt_pk_bf16_f32 v22, v30, v31
	v_lshlrev_b32_e32 v24, 16, v71
	v_and_b32_e32 v25, 0xffff0000, v71
	v_lshlrev_b32_e32 v26, 16, v75
	v_and_b32_e32 v27, 0xffff0000, v75
	v_add_f32_e32 v14, v14, v24
	v_add_f32_e32 v15, v15, v25
	v_mul_f32_e32 v28, 0xbfb8aa3b, v26
	v_mul_f32_e32 v29, 0xbfb8aa3b, v27
	v_exp_f32_e32 v28, v28
	v_exp_f32_e32 v29, v29
	v_fma_f32 v30, v18, v14, -v24
	v_fma_f32 v31, v18, v15, -v25
	v_add_f32_e32 v28, 1.0, v28
	v_add_f32_e32 v29, 1.0, v29
	v_rcp_f32_e32 v28, v28
	v_rcp_f32_e32 v29, v29
	v_mul_f32_e32 v30, v6, v30
	v_mul_f32_e32 v31, v7, v31
	v_mul_f32_e32 v28, v28, v26
	v_mul_f32_e32 v29, v29, v27
	v_mul_f32_e32 v30, v30, v28
	v_mul_f32_e32 v31, v31, v29
	v_cvt_pk_bf16_f32 v23, v30, v31
	global_store_dwordx4 v16, v[20:23], s[8:9] sc1
	s_add_u32 s8, s8, 0x2000
	s_addc_u32 s9, s9, 0
	s_cmp_lt_u32 s23, s11
	s_cbranch_scc1 .Lpq_nolag_4
	v_lshlrev_b32_e32 v24, 16, v76
	v_and_b32_e32 v25, 0xffff0000, v76
	v_sub_f32_e32 v8, v8, v24
	v_sub_f32_e32 v9, v9, v25
	v_lshlrev_b32_e32 v24, 16, v77
	v_and_b32_e32 v25, 0xffff0000, v77
	v_sub_f32_e32 v10, v10, v24
	v_sub_f32_e32 v11, v11, v25
	v_lshlrev_b32_e32 v24, 16, v78
	v_and_b32_e32 v25, 0xffff0000, v78
	v_sub_f32_e32 v12, v12, v24
	v_sub_f32_e32 v13, v13, v25
	v_lshlrev_b32_e32 v24, 16, v79
	v_and_b32_e32 v25, 0xffff0000, v79
	v_sub_f32_e32 v14, v14, v24
	v_sub_f32_e32 v15, v15, v25

; __device__ __forceinline__ unsigned cvt_pk_bf16(float lo, float hi) { unsigned r; asm volatile("v_cvt_pk_bf16_f32 %0, %1, %2" : "=v"(r) : "v"(lo), "v"(hi)); return r; }
; __device__ __forceinline__ float silu_f(float v) { return v * __builtin_amdgcn_rcpf(1.f + __expf(-v)); }
; __device__ __forceinline__ void unpack8(const u32x4 w, float (&f)[8]) { f[0] = bf_lo(w.x); f[1] = bf_hi(w.x); f[2] = bf_lo(w.y); f[3] = bf_hi(w.y); f[4] = bf_lo(w.z); f[5] = bf_hi(w.z); f[6] = bf_lo(w.w); f[7] = bf_hi(w.w); }
; __device__ __forceinline__ void p3_pool(const Params& p) {
;     ...
;         for (int tt = 0; tt < 32; ++tt) {
;             const int t = t0 + tt, pos = pos0 + tt;
;             float u[8], gp[8];
;             unpack8(*(const u32x4*)(proj + (size_t)t * NP2 + P2_U + j0), u);
;             unpack8(*(const u32x4*)(proj + (size_t)t * NP2 + P2_GP + j0), gp);
;             const float icnt = 1.f / (float)min(pos + 1, w);
;             float y[8];
; #pragma unroll
;             for (int j = 0; j < 8; ++j) { sum[j] += u[j]; y[j] = (sum[j] * icnt - u[j]) * ps[j] * silu_f(gp[j]); }
;             u32x4 o; o.x = cvt_pk_bf16(y[0], y[1]); o.y = cvt_pk_bf16(y[2], y[3]); o.z = cvt_pk_bf16(y[4], y[5]); o.w = cvt_pk_bf16(y[6], y[7]);
;             *(u32x4*)(ycat + (size_t)t * DM + 2048 + j0) = o;
;             if (pos - (w - 1) >= 0) { float f[8]; unpack8(*(const u32x4*)(proj + (size_t)(t - (w - 1)) * NP2 + P2_U + j0), f);
; #pragma unroll
;                 for (int j = 0; j < 8; ++j) sum[j] -= f[j]; }
.Lpq_join_5:
	v_lshlrev_b32_e32 v24, 16, v80
	v_and_b32_e32 v25, 0xffff0000, v80
	v_lshlrev_b32_e32 v26, 16, v84
	v_and_b32_e32 v27, 0xffff0000, v84
	v_add_f32_e32 v8, v8, v24
	v_add_f32_e32 v9, v9, v25
	v_mul_f32_e32 v28, 0xbfb8aa3b, v26
	v_mul_f32_e32 v29, 0xbfb8aa3b, v27
	v_exp_f32_e32 v28, v28
	v_exp_f32_e32 v29, v29
	v_fma_f32 v30, v18, v8, -v24
	v_fma_f32 v31, v18, v9, -v25
	v_add_f32_e32 v28, 1.0, v28
	v_add_f32_e32 v29, 1.0, v29
	v_rcp_f32_e32 v28, v28
	v_rcp_f32_e32 v29, v29
	v_mul_f32_e32 v30, v0, v30
	v_mul_f32_e32 v31, v1, v31
	v_mul_f32_e32 v28, v28, v26
	v_mul_f32_e32 v29, v29, v27
	v_mul_f32_e32 v30, v30, v28
	v_mul_f32_e32 v31, v31, v29
	v_cvt_pk_bf16_f32 v20, v30, v31
	v_lshlrev_b32_e32 v24, 16, v81
	v_and_b32_e32 v25, 0xffff0000, v81
	v_lshlrev_b32_e32 v26, 16, v85
	v_and_b32_e32 v27, 0xffff0000, v85
	v_add_f32_e32 v10, v10, v24
	v_add_f32_e32 v11, v11, v25
	v_mul_f32_e32 v28, 0xbfb8aa3b, v26
	v_mul_f32_e32 v29, 0xbfb8aa3b, v27
	v_exp_f32_e32 v28, v28
	v_exp_f32_e32 v29, v29
	v_fma_f32 v30, v18, v10, -v24
	v_fma_f32 v31, v18, v11, -v25
	v_add_f32_e32 v28, 1.0, v28
	v_add_f32_e32 v29, 1.0, v29
	v_rcp_f32_e32 v28, v28
	v_rcp_f32_e32 v29, v29
	v_mul_f32_e32 v30, v2, v30
	v_mul_f32_e32 v31, v3, v31
	v_mul_f32_e32 v28, v28, v26
	v_mul_f32_e32 v29, v29, v27
	v_mul_f32_e32 v30, v30, v28
	v_mul_f32_e32 v31, v31, v29
	v_cvt_pk_bf16_f32 v21, v30, v31
	v_lshlrev_b32_e32 v24, 16, v82
	v_and_b32_e32 v25, 0xffff0000, v82
	v_lshlrev_b32_e32 v26, 16, v86
	v_and_b32_e32 v27, 0xffff0000, v86
	v_add_f32_e32 v12, v12, v24
	v_add_f32_e32 v13, v13, v25
	v_mul_f32_e32 v28, 0xbfb8aa3b, v26
	v_mul_f32_e32 v29, 0xbfb8aa3b, v27
	v_exp_f32_e32 v28, v28
	v_exp_f32_e32 v29, v29
	v_fma_f32 v30, v18, v12, -v24
	v_fma_f32 v31, v18, v13, -v25
	v_add_f32_e32 v28, 1.0, v28
	v_add_f32_e32 v29, 1.0, v29
	v_rcp_f32_e32 v28, v28
	v_rcp_f32_e32 v29, v29
	v_mul_f32_e32 v30, v4, v30
	v_mul_f32_e32 v31, v5, v31
	v_mul_f32_e32 v28, v28, v26
	v_mul_f32_e32 v29, v29, v27
	v_mul_f32_e32 v30, v30, v28
	v_mul_f32_e32 v31, v31, v29
	v_cvt_pk_bf16_f32 v22, v30, v31
	v_lshlrev_b32_e32 v24, 16, v83
	v_and_b32_e32 v25, 0xffff0000, v83
	v_lshlrev_b32_e32 v26, 16, v87
	v_and_b32_e32 v27, 0xffff0000, v87
	v_add_f32_e32 v14, v14, v24
	v_add_f32_e32 v15, v15, v25
	v_mul_f32_e32 v28, 0xbfb8aa3b, v26
	v_mul_f32_e32 v29, 0xbfb8aa3b, v27
	v_exp_f32_e32 v28, v28
	v_exp_f32_e32 v29, v29
	v_fma_f32 v30, v18, v14, -v24
	v_fma_f32 v31, v18, v15, -v25
	v_add_f32_e32 v28, 1.0, v28
	v_add_f32_e32 v29, 1.0, v29
	v_rcp_f32_e32 v28, v28
	v_rcp_f32_e32 v29, v29
	v_mul_f32_e32 v30, v6, v30
	v_mul_f32_e32 v31, v7, v31
	v_mul_f32_e32 v28, v28, v26
	v_mul_f32_e32 v29, v29, v27
	v_mul_f32_e32 v30, v30, v28
	v_mul_f32_e32 v31, v31, v29
	v_cvt_pk_bf16_f32 v23, v30, v31
	global_store_dwordx4 v16, v[20:23], s[8:9] sc1
	s_add_u32 s8, s8, 0x2000
	s_addc_u32 s9, s9, 0
	s_cmp_lt_u32 s23, s11
	s_cbranch_scc1 .Lpq_nolag_5
	v_lshlrev_b32_e32 v24, 16, v88
	v_and_b32_e32 v25, 0xffff0000, v88
	v_sub_f32_e32 v8, v8, v24
	v_sub_f32_e32 v9, v9, v25
	v_lshlrev_b32_e32 v24, 16, v89
	v_and_b32_e32 v25, 0xffff0000, v89
	v_sub_f32_e32 v10, v10, v24
	v_sub_f32_e32 v11, v11, v25
	v_lshlrev_b32_e32 v24, 16, v90
	v_and_b32_e32 v25, 0xffff0000, v90
	v_sub_f32_e32 v12, v12, v24
	v_sub_f32_e32 v13, v13, v25
	v_lshlrev_b32_e32 v24, 16, v91
	v_and_b32_e32 v25, 0xffff0000, v91
	v_sub_f32_e32 v14, v14, v24
	v_sub_f32_e32 v15, v15, v25

; __device__ __forceinline__ unsigned cvt_pk_bf16(float lo, float hi) { unsigned r; asm volatile("v_cvt_pk_bf16_f32 %0, %1, %2" : "=v"(r) : "v"(lo), "v"(hi)); return r; }
; __device__ __forceinline__ float silu_f(float v) { return v * __builtin_amdgcn_rcpf(1.f + __expf(-v)); }
; __device__ __forceinline__ void unpack8(const u32x4 w, float (&f)[8]) { f[0] = bf_lo(w.x); f[1] = bf_hi(w.x); f[2] = bf_lo(w.y); f[3] = bf_hi(w.y); f[4] = bf_lo(w.z); f[5] = bf_hi(w.z); f[6] = bf_lo(w.w); f[7] = bf_hi(w.w); }
; __device__ __forceinline__ void p3_pool(const Params& p) {
;     ...
;         for (int tt = 0; tt < 32; ++tt) {
;             const int t = t0 + tt, pos = pos0 + tt;
;             float u[8], gp[8];
;             unpack8(*(const u32x4*)(proj + (size_t)t * NP2 + P2_U + j0), u);
;             unpack8(*(const u32x4*)(proj + (size_t)t * NP2 + P2_GP + j0), gp);
;             const float icnt = 1.f / (float)min(pos + 1, w);
;             float y[8];
; #pragma unroll
;             for (int j = 0; j < 8; ++j) { sum[j] += u[j]; y[j] = (sum[j] * icnt - u[j]) * ps[j] * silu_f(gp[j]); }
;             u32x4 o; o.x = cvt_pk_bf16(y[0], y[1]); o.y = cvt_pk_bf16(y[2], y[3]); o.z = cvt_pk_bf16(y[4], y[5]); o.w = cvt_pk_bf16(y[6], y[7]);
;             *(u32x4*)(ycat + (size_t)t * DM + 2048 + j0) = o;
;             if (pos - (w - 1) >= 0) { float f[8]; unpack8(*(const u32x4*)(proj + (size_t)(t - (w - 1)) * NP2 + P2_U + j0), f);
; #pragma unroll
;                 for (int j = 0; j < 8; ++j) sum[j] -= f[j]; }
.Lpq_join_6:
	v_lshlrev_b32_e32 v24, 16, v92
	v_and_b32_e32 v25, 0xffff0000, v92
	v_lshlrev_b32_e32 v26, 16, v96
	v_and_b32_e32 v27, 0xffff0000, v96
	v_add_f32_e32 v8, v8, v24
	v_add_f32_e32 v9, v9, v25
	v_mul_f32_e32 v28, 0xbfb8aa3b, v26
	v_mul_f32_e32 v29, 0xbfb8aa3b, v27
	v_exp_f32_e32 v28, v28
	v_exp_f32_e32 v29, v29
	v_fma_f32 v30, v18, v8, -v24
	v_fma_f32 v31, v18, v9, -v25
	v_add_f32_e32 v28, 1.0, v28
	v_add_f32_e32 v29, 1.0, v29
	v_rcp_f32_e32 v28, v28
	v_rcp_f32_e32 v29, v29
	v_mul_f32_e32 v30, v0, v30
	v_mul_f32_e32 v31, v1, v31
	v_mul_f32_e32 v28, v28, v26
	v_mul_f32_e32 v29, v29, v27
	v_mul_f32_e32 v30, v30, v28
	v_mul_f32_e32 v31, v31, v29
	v_cvt_pk_bf16_f32 v20, v30, v31
	v_lshlrev_b32_e32 v24, 16, v93
	v_and_b32_e32 v25, 0xffff0000, v93
	v_lshlrev_b32_e32 v26, 16, v97
	v_and_b32_e32 v27, 0xffff0000, v97
	v_add_f32_e32 v10, v10, v24
	v_add_f32_e32 v11, v11, v25
	v_mul_f32_e32 v28, 0xbfb8aa3b, v26
	v_mul_f32_e32 v29, 0xbfb8aa3b, v27
	v_exp_f32_e32 v28, v28
	v_exp_f32_e32 v29, v29
	v_fma_f32 v30, v18, v10, -v24
	v_fma_f32 v31, v18, v11, -v25
	v_add_f32_e32 v28, 1.0, v28
	v_add_f32_e32 v29, 1.0, v29
	v_rcp_f32_e32 v28, v28
	v_rcp_f32_e32 v29, v29
	v_mul_f32_e32 v30, v2, v30
	v_mul_f32_e32 v31, v3, v31
	v_mul_f32_e32 v28, v28, v26
	v_mul_f32_e32 v29, v29, v27
	v_mul_f32_e32 v30, v30, v28
	v_mul_f32_e32 v31, v31, v29
	v_cvt_pk_bf16_f32 v21, v30, v31
	v_lshlrev_b32_e32 v24, 16, v94
	v_and_b32_e32 v25, 0xffff0000, v94
	v_lshlrev_b32_e32 v26, 16, v98
	v_and_b32_e32 v27, 0xffff0000, v98
	v_add_f32_e32 v12, v12, v24
	v_add_f32_e32 v13, v13, v25
	v_mul_f32_e32 v28, 0xbfb8aa3b, v26
	v_mul_f32_e32 v29, 0xbfb8aa3b, v27
	v_exp_f32_e32 v28, v28
	v_exp_f32_e32 v29, v29
	v_fma_f32 v30, v18, v12, -v24
	v_fma_f32 v31, v18, v13, -v25
	v_add_f32_e32 v28, 1.0, v28
	v_add_f32_e32 v29, 1.0, v29
	v_rcp_f32_e32 v28, v28
	v_rcp_f32_e32 v29, v29
	v_mul_f32_e32 v30, v4, v30
	v_mul_f32_e32 v31, v5, v31
	v_mul_f32_e32 v28, v28, v26
	v_mul_f32_e32 v29, v29, v27
	v_mul_f32_e32 v30, v30, v28
	v_mul_f32_e32 v31, v31, v29
	v_cvt_pk_bf16_f32 v22, v30, v31
	v_lshlrev_b32_e32 v24, 16, v95
	v_and_b32_e32 v25, 0xffff0000, v95
	v_lshlrev_b32_e32 v26, 16, v99
	v_and_b32_e32 v27, 0xffff0000, v99
	v_add_f32_e32 v14, v14, v24
	v_add_f32_e32 v15, v15, v25
	v_mul_f32_e32 v28, 0xbfb8aa3b, v26
	v_mul_f32_e32 v29, 0xbfb8aa3b, v27
	v_exp_f32_e32 v28, v28
	v_exp_f32_e32 v29, v29
	v_fma_f32 v30, v18, v14, -v24
	v_fma_f32 v31, v18, v15, -v25
	v_add_f32_e32 v28, 1.0, v28
	v_add_f32_e32 v29, 1.0, v29
	v_rcp_f32_e32 v28, v28
	v_rcp_f32_e32 v29, v29
	v_mul_f32_e32 v30, v6, v30
	v_mul_f32_e32 v31, v7, v31
	v_mul_f32_e32 v28, v28, v26
	v_mul_f32_e32 v29, v29, v27
	v_mul_f32_e32 v30, v30, v28
	v_mul_f32_e32 v31, v31, v29
	v_cvt_pk_bf16_f32 v23, v30, v31
	global_store_dwordx4 v16, v[20:23], s[8:9] sc1
	s_add_u32 s8, s8, 0x2000
	s_addc_u32 s9, s9, 0
	s_cmp_lt_u32 s23, s11
	s_cbranch_scc1 .Lpq_nolag_6
	v_lshlrev_b32_e32 v24, 16, v100
	v_and_b32_e32 v25, 0xffff0000, v100
	v_sub_f32_e32 v8, v8, v24
	v_sub_f32_e32 v9, v9, v25
	v_lshlrev_b32_e32 v24, 16, v101
	v_and_b32_e32 v25, 0xffff0000, v101
	v_sub_f32_e32 v10, v10, v24
	v_sub_f32_e32 v11, v11, v25
	v_lshlrev_b32_e32 v24, 16, v102
	v_and_b32_e32 v25, 0xffff0000, v102
	v_sub_f32_e32 v12, v12, v24
	v_sub_f32_e32 v13, v13, v25
	v_lshlrev_b32_e32 v24, 16, v103
	v_and_b32_e32 v25, 0xffff0000, v103
	v_sub_f32_e32 v14, v14, v24
	v_sub_f32_e32 v15, v15, v25

; __device__ __forceinline__ unsigned cvt_pk_bf16(float lo, float hi) { unsigned r; asm volatile("v_cvt_pk_bf16_f32 %0, %1, %2" : "=v"(r) : "v"(lo), "v"(hi)); return r; }
; __device__ __forceinline__ float silu_f(float v) { return v * __builtin_amdgcn_rcpf(1.f + __expf(-v)); }
; __device__ __forceinline__ void unpack8(const u32x4 w, float (&f)[8]) { f[0] = bf_lo(w.x); f[1] = bf_hi(w.x); f[2] = bf_lo(w.y); f[3] = bf_hi(w.y); f[4] = bf_lo(w.z); f[5] = bf_hi(w.z); f[6] = bf_lo(w.w); f[7] = bf_hi(w.w); }
; __device__ __forceinline__ void p3_pool(const Params& p) {
;     ...
;         for (int tt = 0; tt < 32; ++tt) {
;             const int t = t0 + tt, pos = pos0 + tt;
;             float u[8], gp[8];
;             unpack8(*(const u32x4*)(proj + (size_t)t * NP2 + P2_U + j0), u);
;             unpack8(*(const u32x4*)(proj + (size_t)t * NP2 + P2_GP + j0), gp);
;             const float icnt = 1.f / (float)min(pos + 1, w);
;             float y[8];
; #pragma unroll
;             for (int j = 0; j < 8; ++j) { sum[j] += u[j]; y[j] = (sum[j] * icnt - u[j]) * ps[j] * silu_f(gp[j]); }
;             u32x4 o; o.x = cvt_pk_bf16(y[0], y[1]); o.y = cvt_pk_bf16(y[2], y[3]); o.z = cvt_pk_bf16(y[4], y[5]); o.w = cvt_pk_bf16(y[6], y[7]);
;             *(u32x4*)(ycat + (size_t)t * DM + 2048 + j0) = o;
;             if (pos - (w - 1) >= 0) { float f[8]; unpack8(*(const u32x4*)(proj + (size_t)(t - (w - 1)) * NP2 + P2_U + j0), f);
; #pragma unroll
;                 for (int j = 0; j < 8; ++j) sum[j] -= f[j]; }
.Lpq_join_7:
	v_lshlrev_b32_e32 v24, 16, v104
	v_and_b32_e32 v25, 0xffff0000, v104
	v_lshlrev_b32_e32 v26, 16, v108
	v_and_b32_e32 v27, 0xffff0000, v108
	v_add_f32_e32 v8, v8, v24
	v_add_f32_e32 v9, v9, v25
	v_mul_f32_e32 v28, 0xbfb8aa3b, v26
	v_mul_f32_e32 v29, 0xbfb8aa3b, v27
	v_exp_f32_e32 v28, v28
	v_exp_f32_e32 v29, v29
	v_fma_f32 v30, v18, v8, -v24
	v_fma_f32 v31, v18, v9, -v25
	v_add_f32_e32 v28, 1.0, v28
	v_add_f32_e32 v29, 1.0, v29
	v_rcp_f32_e32 v28, v28
	v_rcp_f32_e32 v29, v29
	v_mul_f32_e32 v30, v0, v30
	v_mul_f32_e32 v31, v1, v31
	v_mul_f32_e32 v28, v28, v26
	v_mul_f32_e32 v29, v29, v27
	v_mul_f32_e32 v30, v30, v28
	v_mul_f32_e32 v31, v31, v29
	v_cvt_pk_bf16_f32 v20, v30, v31
	v_lshlrev_b32_e32 v24, 16, v105
	v_and_b32_e32 v25, 0xffff0000, v105
	v_lshlrev_b32_e32 v26, 16, v109
	v_and_b32_e32 v27, 0xffff0000, v109
	v_add_f32_e32 v10, v10, v24
	v_add_f32_e32 v11, v11, v25
	v_mul_f32_e32 v28, 0xbfb8aa3b, v26
	v_mul_f32_e32 v29, 0xbfb8aa3b, v27
	v_exp_f32_e32 v28, v28
	v_exp_f32_e32 v29, v29
	v_fma_f32 v30, v18, v10, -v24
	v_fma_f32 v31, v18, v11, -v25
	v_add_f32_e32 v28, 1.0, v28
	v_add_f32_e32 v29, 1.0, v29
	v_rcp_f32_e32 v28, v28
	v_rcp_f32_e32 v29, v29
	v_mul_f32_e32 v30, v2, v30
	v_mul_f32_e32 v31, v3, v31
	v_mul_f32_e32 v28, v28, v26
	v_mul_f32_e32 v29, v29, v27
	v_mul_f32_e32 v30, v30, v28
	v_mul_f32_e32 v31, v31, v29
	v_cvt_pk_bf16_f32 v21, v30, v31
	v_lshlrev_b32_e32 v24, 16, v106
	v_and_b32_e32 v25, 0xffff0000, v106
	v_lshlrev_b32_e32 v26, 16, v110
	v_and_b32_e32 v27, 0xffff0000, v110
	v_add_f32_e32 v12, v12, v24
	v_add_f32_e32 v13, v13, v25
	v_mul_f32_e32 v28, 0xbfb8aa3b, v26
	v_mul_f32_e32 v29, 0xbfb8aa3b, v27
	v_exp_f32_e32 v28, v28
	v_exp_f32_e32 v29, v29
	v_fma_f32 v30, v18, v12, -v24
	v_fma_f32 v31, v18, v13, -v25
	v_add_f32_e32 v28, 1.0, v28
	v_add_f32_e32 v29, 1.0, v29
	v_rcp_f32_e32 v28, v28
	v_rcp_f32_e32 v29, v29
	v_mul_f32_e32 v30, v4, v30
	v_mul_f32_e32 v31, v5, v31
	v_mul_f32_e32 v28, v28, v26
	v_mul_f32_e32 v29, v29, v27
	v_mul_f32_e32 v30, v30, v28
	v_mul_f32_e32 v31, v31, v29
	v_cvt_pk_bf16_f32 v22, v30, v31
	v_lshlrev_b32_e32 v24, 16, v107
	v_and_b32_e32 v25, 0xffff0000, v107
	v_lshlrev_b32_e32 v26, 16, v111
	v_and_b32_e32 v27, 0xffff0000, v111
	v_add_f32_e32 v14, v14, v24
	v_add_f32_e32 v15, v15, v25
	v_mul_f32_e32 v28, 0xbfb8aa3b, v26
	v_mul_f32_e32 v29, 0xbfb8aa3b, v27
	v_exp_f32_e32 v28, v28
	v_exp_f32_e32 v29, v29
	v_fma_f32 v30, v18, v14, -v24
	v_fma_f32 v31, v18, v15, -v25
	v_add_f32_e32 v28, 1.0, v28
	v_add_f32_e32 v29, 1.0, v29
	v_rcp_f32_e32 v28, v28
	v_rcp_f32_e32 v29, v29
	v_mul_f32_e32 v30, v6, v30
	v_mul_f32_e32 v31, v7, v31
	v_mul_f32_e32 v28, v28, v26
	v_mul_f32_e32 v29, v29, v27
	v_mul_f32_e32 v30, v30, v28
	v_mul_f32_e32 v31, v31, v29
	v_cvt_pk_bf16_f32 v23, v30, v31
	global_store_dwordx4 v16, v[20:23], s[8:9] sc1
	s_add_u32 s8, s8, 0x2000
	s_addc_u32 s9, s9, 0
	s_cmp_lt_u32 s23, s11
	s_cbranch_scc1 .Lpq_nolag_7
	v_lshlrev_b32_e32 v24, 16, v112
	v_and_b32_e32 v25, 0xffff0000, v112
	v_sub_f32_e32 v8, v8, v24
	v_sub_f32_e32 v9, v9, v25
	v_lshlrev_b32_e32 v24, 16, v113
	v_and_b32_e32 v25, 0xffff0000, v113
	v_sub_f32_e32 v10, v10, v24
	v_sub_f32_e32 v11, v11, v25
	v_lshlrev_b32_e32 v24, 16, v114
	v_and_b32_e32 v25, 0xffff0000, v114
	v_sub_f32_e32 v12, v12, v24
	v_sub_f32_e32 v13, v13, v25
	v_lshlrev_b32_e32 v24, 16, v115
	v_and_b32_e32 v25, 0xffff0000, v115
	v_sub_f32_e32 v14, v14, v24
	v_sub_f32_e32 v15, v15, v25

; __device__ __forceinline__ unsigned cvt_pk_bf16(float lo, float hi) { unsigned r; asm volatile("v_cvt_pk_bf16_f32 %0, %1, %2" : "=v"(r) : "v"(lo), "v"(hi)); return r; }
; __device__ __forceinline__ float silu_f(float v) { return v * __builtin_amdgcn_rcpf(1.f + __expf(-v)); }
; __device__ __forceinline__ void unpack8(const u32x4 w, float (&f)[8]) { f[0] = bf_lo(w.x); f[1] = bf_hi(w.x); f[2] = bf_lo(w.y); f[3] = bf_hi(w.y); f[4] = bf_lo(w.z); f[5] = bf_hi(w.z); f[6] = bf_lo(w.w); f[7] = bf_hi(w.w); }
; __device__ __forceinline__ void p3_pool(const Params& p) {
;     ...
;         for (int tt = 0; tt < 32; ++tt) {
;             const int t = t0 + tt, pos = pos0 + tt;
;             float u[8], gp[8];
;             unpack8(*(const u32x4*)(proj + (size_t)t * NP2 + P2_U + j0), u);
;             unpack8(*(const u32x4*)(proj + (size_t)t * NP2 + P2_GP + j0), gp);
;             const float icnt = 1.f / (float)min(pos + 1, w);
;             float y[8];
; #pragma unroll
;             for (int j = 0; j < 8; ++j) { sum[j] += u[j]; y[j] = (sum[j] * icnt - u[j]) * ps[j] * silu_f(gp[j]); }
;             u32x4 o; o.x = cvt_pk_bf16(y[0], y[1]); o.y = cvt_pk_bf16(y[2], y[3]); o.z = cvt_pk_bf16(y[4], y[5]); o.w = cvt_pk_bf16(y[6], y[7]);
;             *(u32x4*)(ycat + (size_t)t * DM + 2048 + j0) = o;
;             if (pos - (w - 1) >= 0) { float f[8]; unpack8(*(const u32x4*)(proj + (size_t)(t - (w - 1)) * NP2 + P2_U + j0), f);
; #pragma unroll
;                 for (int j = 0; j < 8; ++j) sum[j] -= f[j]; }
.Lpq_join_8:
	v_lshlrev_b32_e32 v24, 16, v116
	v_and_b32_e32 v25, 0xffff0000, v116
	v_lshlrev_b32_e32 v26, 16, v120
	v_and_b32_e32 v27, 0xffff0000, v120
	v_add_f32_e32 v8, v8, v24
	v_add_f32_e32 v9, v9, v25
	v_mul_f32_e32 v28, 0xbfb8aa3b, v26
	v_mul_f32_e32 v29, 0xbfb8aa3b, v27
	v_exp_f32_e32 v28, v28
	v_exp_f32_e32 v29, v29
	v_fma_f32 v30, v18, v8, -v24
	v_fma_f32 v31, v18, v9, -v25
	v_add_f32_e32 v28, 1.0, v28
	v_add_f32_e32 v29, 1.0, v29
	v_rcp_f32_e32 v28, v28
	v_rcp_f32_e32 v29, v29
	v_mul_f32_e32 v30, v0, v30
	v_mul_f32_e32 v31, v1, v31
	v_mul_f32_e32 v28, v28, v26
	v_mul_f32_e32 v29, v29, v27
	v_mul_f32_e32 v30, v30, v28
	v_mul_f32_e32 v31, v31, v29
	v_cvt_pk_bf16_f32 v20, v30, v31
	v_lshlrev_b32_e32 v24, 16, v117
	v_and_b32_e32 v25, 0xffff0000, v117
	v_lshlrev_b32_e32 v26, 16, v121
	v_and_b32_e32 v27, 0xffff0000, v121
	v_add_f32_e32 v10, v10, v24
	v_add_f32_e32 v11, v11, v25
	v_mul_f32_e32 v28, 0xbfb8aa3b, v26
	v_mul_f32_e32 v29, 0xbfb8aa3b, v27
	v_exp_f32_e32 v28, v28
	v_exp_f32_e32 v29, v29
	v_fma_f32 v30, v18, v10, -v24
	v_fma_f32 v31, v18, v11, -v25
	v_add_f32_e32 v28, 1.0, v28
	v_add_f32_e32 v29, 1.0, v29
	v_rcp_f32_e32 v28, v28
	v_rcp_f32_e32 v29, v29
	v_mul_f32_e32 v30, v2, v30
	v_mul_f32_e32 v31, v3, v31
	v_mul_f32_e32 v28, v28, v26
	v_mul_f32_e32 v29, v29, v27
	v_mul_f32_e32 v30, v30, v28
	v_mul_f32_e32 v31, v31, v29
	v_cvt_pk_bf16_f32 v21, v30, v31
	v_lshlrev_b32_e32 v24, 16, v118
	v_and_b32_e32 v25, 0xffff0000, v118
	v_lshlrev_b32_e32 v26, 16, v122
	v_and_b32_e32 v27, 0xffff0000, v122
	v_add_f32_e32 v12, v12, v24
	v_add_f32_e32 v13, v13, v25
	v_mul_f32_e32 v28, 0xbfb8aa3b, v26
	v_mul_f32_e32 v29, 0xbfb8aa3b, v27
	v_exp_f32_e32 v28, v28
	v_exp_f32_e32 v29, v29
	v_fma_f32 v30, v18, v12, -v24
	v_fma_f32 v31, v18, v13, -v25
	v_add_f32_e32 v28, 1.0, v28
	v_add_f32_e32 v29, 1.0, v29
	v_rcp_f32_e32 v28, v28
	v_rcp_f32_e32 v29, v29
	v_mul_f32_e32 v30, v4, v30
	v_mul_f32_e32 v31, v5, v31
	v_mul_f32_e32 v28, v28, v26
	v_mul_f32_e32 v29, v29, v27
	v_mul_f32_e32 v30, v30, v28
	v_mul_f32_e32 v31, v31, v29
	v_cvt_pk_bf16_f32 v22, v30, v31
	v_lshlrev_b32_e32 v24, 16, v119
	v_and_b32_e32 v25, 0xffff0000, v119
	v_lshlrev_b32_e32 v26, 16, v123
	v_and_b32_e32 v27, 0xffff0000, v123
	v_add_f32_e32 v14, v14, v24
	v_add_f32_e32 v15, v15, v25
	v_mul_f32_e32 v28, 0xbfb8aa3b, v26
	v_mul_f32_e32 v29, 0xbfb8aa3b, v27
	v_exp_f32_e32 v28, v28
	v_exp_f32_e32 v29, v29
	v_fma_f32 v30, v18, v14, -v24
	v_fma_f32 v31, v18, v15, -v25
	v_add_f32_e32 v28, 1.0, v28
	v_add_f32_e32 v29, 1.0, v29
	v_rcp_f32_e32 v28, v28
	v_rcp_f32_e32 v29, v29
	v_mul_f32_e32 v30, v6, v30
	v_mul_f32_e32 v31, v7, v31
	v_mul_f32_e32 v28, v28, v26
	v_mul_f32_e32 v29, v29, v27
	v_mul_f32_e32 v30, v30, v28
	v_mul_f32_e32 v31, v31, v29
	v_cvt_pk_bf16_f32 v23, v30, v31
	global_store_dwordx4 v16, v[20:23], s[8:9] sc1
	s_add_u32 s8, s8, 0x2000
	s_addc_u32 s9, s9, 0
	s_cmp_lt_u32 s23, s11
	s_cbranch_scc1 .Lpq_nolag_8
	v_lshlrev_b32_e32 v24, 16, v124
	v_and_b32_e32 v25, 0xffff0000, v124
	v_sub_f32_e32 v8, v8, v24
	v_sub_f32_e32 v9, v9, v25
	v_lshlrev_b32_e32 v24, 16, v125
	v_and_b32_e32 v25, 0xffff0000, v125
	v_sub_f32_e32 v10, v10, v24
	v_sub_f32_e32 v11, v11, v25
	v_lshlrev_b32_e32 v24, 16, v126
	v_and_b32_e32 v25, 0xffff0000, v126
	v_sub_f32_e32 v12, v12, v24
	v_sub_f32_e32 v13, v13, v25
	v_lshlrev_b32_e32 v24, 16, v127
	v_and_b32_e32 v25, 0xffff0000, v127
	v_sub_f32_e32 v14, v14, v24
	v_sub_f32_e32 v15, v15, v25

; __device__ __forceinline__ unsigned cvt_pk_bf16(float lo, float hi) { unsigned r; asm volatile("v_cvt_pk_bf16_f32 %0, %1, %2" : "=v"(r) : "v"(lo), "v"(hi)); return r; }
; __device__ __forceinline__ void attn_passes(const Params& p, LAS unsigned char* lds) {
;     ...
;             float lt = lsum; lt += __shfl_xor(lt, 16); lt += __shfl_xor(lt, 32);
; #pragma unroll
;             for (int c = 0; c < 8; c += 2) {
;                 unsigned ax = cvt_pk_bf16(o[c][0], o[c][1]), ay = cvt_pk_bf16(o[c][2], o[c][3]), bx = cvt_pk_bf16(o[c + 1][0], o[c + 1][1]), by = cvt_pk_bf16(o[c + 1][2], o[c + 1][3]);
;                 const auto rx = __builtin_amdgcn_permlane16_swap(ax, bx, false, false); const auto ry = __builtin_amdgcn_permlane16_swap(ay, by, false, false);
;                 u32x4 sw; sw.x = rx[0]; sw.y = ry[0]; sw.z = rx[1]; sw.w = ry[1];
;                 *(u32x4*)(ob_bh + tq * 2048 + 16 * (c + (g & 1)) + 8 * (g >> 1)) = sw; }
;             if (g == 0) { ml_bh[tq * 32] = m; ml_bh[tq * 32 + 1] = lt; }
.LBB0_314:
	s_nop 1
	v_add_f32_e32 v16, 0, v65
	v_add_f32_e32 v16, v66, v16
	v_add_f32_e32 v16, v67, v16
	v_add_f32_e32 v16, v68, v16
	v_add_f32_e32 v16, v69, v16
	v_add_f32_e32 v16, v70, v16
	v_add_f32_e32 v16, v71, v16
	v_add_f32_e32 v16, v72, v16
	v_add_f32_e32 v18, v64, v16
	v_mov_b32_e32 v19, v18
	v_lshlrev_b64 v[16:17], s87, v[90:91]
	v_lshl_add_u64 v[16:17], v[16:17], 0, s[22:23]
	s_barrier
	v_lshlrev_b64 v[24:25], 12, v[16:17]
	v_cvt_pk_bf16_f32 v20, v44, v45
	v_cvt_pk_bf16_f32 v21, v46, v47
	v_cvt_pk_bf16_f32 v22, v40, v41
	v_cvt_pk_bf16_f32 v23, v42, v43
	v_lshl_add_u64 v[24:25], v[156:157], 0, v[24:25]
	v_permlane16_swap_b32_e32 v20, v22
	v_permlane16_swap_b32_e32 v21, v23
	v_permlane16_swap_b32_e32 v18, v19
	v_add_f32_e32 v18, v18, v19
	global_store_dwordx4 v[24:25], v[20:23], off sc1
	v_mov_b32_e32 v19, v18
	v_mov_b32_e32 v161, v18
	s_nop 0
	v_cvt_pk_bf16_f32 v20, v36, v37
	v_cvt_pk_bf16_f32 v21, v38, v39
	v_cvt_pk_bf16_f32 v22, v32, v33
	v_cvt_pk_bf16_f32 v23, v34, v35
	s_nop 0
	v_permlane16_swap_b32_e32 v20, v22
	v_permlane16_swap_b32_e32 v21, v23
	global_store_dwordx4 v[24:25], v[20:23], off offset:64 sc1
	v_cvt_pk_bf16_f32 v12, v12, v13
	v_cvt_pk_bf16_f32 v13, v14, v15
	v_cvt_pk_bf16_f32 v14, v8, v9
	v_cvt_pk_bf16_f32 v15, v10, v11
	s_nop 0
	v_permlane16_swap_b32_e32 v12, v14
	v_permlane16_swap_b32_e32 v13, v15
	global_store_dwordx4 v[24:25], v[12:15], off offset:128 sc1
	v_cvt_pk_bf16_f32 v4, v4, v5
	v_cvt_pk_bf16_f32 v5, v6, v7
	v_cvt_pk_bf16_f32 v6, v0, v1
	v_cvt_pk_bf16_f32 v7, v2, v3
	s_nop 0
	v_permlane16_swap_b32_e32 v4, v6
	v_permlane16_swap_b32_e32 v5, v7
	global_store_dwordx4 v[24:25], v[4:7], off offset:192 sc1
	v_permlane32_swap_b32_e32 v161, v19
	s_and_saveexec_b64 s[6:7], s[4:5]
	s_cbranch_execz .LBB0_256
	v_lshlrev_b64 v[0:1], 7, v[16:17]
	v_lshl_add_u64 v[0:1], s[48:49], 0, v[0:1]
	s_waitcnt lgkmcnt(0)
	v_add_f32_e32 v161, v18, v19
	global_store_dwordx2 v[0:1], v[160:161], off
	s_branch .LBB0_256

; __device__ __forceinline__ unsigned cvt_pk_bf16(float lo, float hi) { unsigned r; asm volatile("v_cvt_pk_bf16_f32 %0, %1, %2" : "=v"(r) : "v"(lo), "v"(hi)); return r; }
; __device__ __forceinline__ float silu_f(float v) { return v * __builtin_amdgcn_rcpf(1.f + __expf(-v)); }
; __device__ __forceinline__ void unpack8(const u32x4 w, float (&f)[8]) { f[0] = bf_lo(w.x); f[1] = bf_hi(w.x); f[2] = bf_lo(w.y); f[3] = bf_hi(w.y); f[4] = bf_lo(w.z); f[5] = bf_hi(w.z); f[6] = bf_lo(w.w); f[7] = bf_hi(w.w); }
; __device__ __forceinline__ void p3_combine(const Params& p) {
;     ...
;     for (int t = blockIdx.x * 2 + sub; t < MTOK; t += gridDim.x * 2) {
;         float mp[3], lp[3];
; #pragma unroll
;         for (int q = 0; q < 3; ++q) { const float* mq = ml + ((size_t)q * MTOK + t) * 32 + h * 2; mp[q] = mq[0]; lp[q] = mq[1]; }
;         const float mm = fmaxf(mp[0], fmaxf(mp[1], mp[2]));
;         float num[8], den = 0.f;
; #pragma unroll
;         for (int j = 0; j < 8; ++j) num[j] = 0.f;
; #pragma unroll
;         for (int q = 0; q < 3; ++q) { const float wq = __builtin_amdgcn_exp2f(mp[q] - mm); den += wq * lp[q];
;             float f[8]; unpack8(*(const u32x4*)(ob + ((size_t)q * MTOK + t) * 2048 + j0), f);
; #pragma unroll
;             for (int j = 0; j < 8; ++j) num[j] += wq * f[j]; }
;         const float inv = 1.f / den;
;         float ga[8]; unpack8(*(const u32x4*)(proj2 + (size_t)t * NP2 + P2_GA + j0), ga);
;         float y[8];
; #pragma unroll
;         for (int j = 0; j < 8; ++j) y[j] = num[j] * inv * silu_f(ga[j]);
;         u32x4 o; o.x = cvt_pk_bf16(y[0], y[1]); o.y = cvt_pk_bf16(y[2], y[3]); o.z = cvt_pk_bf16(y[4], y[5]); o.w = cvt_pk_bf16(y[6], y[7]);
;         *(u32x4*)(ycat + (size_t)t * DM + j0) = o;
;     }
.LBB0_389:
	v_ashrrev_i32_e32 v1, 31, v0
	v_lshlrev_b64 v[10:11], 7, v[0:1]
	v_lshl_add_u64 v[22:23], v[2:3], 0, v[10:11]
	v_lshlrev_b64 v[10:11], 12, v[0:1]
	v_lshl_add_u64 v[14:15], v[4:5], 0, v[10:11]
	v_add_co_u32_e32 v24, vcc, s9, v14
	global_load_dwordx4 v[10:13], v[14:15], off
	s_nop 0
	v_addc_co_u32_e32 v25, vcc, 0, v15, vcc
	v_add_co_u32_e32 v26, vcc, s10, v14
	s_waitcnt vmcnt(0)
	v_lshlrev_b32_e32 v40, 16, v11
	v_addc_co_u32_e32 v27, vcc, 0, v15, vcc
	global_load_dwordx4 v[14:17], v[26:27], off
	global_load_dwordx4 v[18:21], v[24:25], off
	v_add_co_u32_e32 v24, vcc, 0x200000, v22
	v_and_b32_e32 v41, 0xffff0000, v11
	s_nop 0
	v_addc_co_u32_e32 v25, vcc, 0, v23, vcc
	v_add_co_u32_e32 v26, vcc, 0x400000, v22
	v_lshlrev_b32_e32 v44, 16, v13
	s_nop 0
	v_addc_co_u32_e32 v27, vcc, 0, v23, vcc
	global_load_dwordx2 v[28:29], v[22:23], off
	global_load_dwordx2 v[30:31], v[24:25], off
	global_load_dwordx2 v[32:33], v[26:27], off
	v_mad_i64_i32 v[22:23], s[20:21], v0, s11, v[6:7]
	global_load_dwordx4 v[22:25], v[22:23], off
	v_and_b32_e32 v45, 0xffff0000, v13
	v_lshlrev_b32_e32 v38, 16, v10
	v_and_b32_e32 v39, 0xffff0000, v10
	v_lshlrev_b32_e32 v42, 16, v12
	v_and_b32_e32 v43, 0xffff0000, v12
	s_waitcnt vmcnt(5)
	v_lshlrev_b32_e32 v11, 16, v14
	v_and_b32_e32 v13, 0xffff0000, v14
	s_waitcnt vmcnt(4)
	v_lshlrev_b32_e32 v26, 16, v19
	v_and_b32_e32 v14, 0xffff0000, v19
	v_lshlrev_b32_e32 v19, 16, v16
	v_and_b32_e32 v35, 0xffff0000, v16
	v_lshlrev_b32_e32 v10, 16, v18
	v_and_b32_e32 v12, 0xffff0000, v18
	v_lshlrev_b32_e32 v18, 16, v20
	v_and_b32_e32 v34, 0xffff0000, v20
	v_lshlrev_b32_e32 v37, 16, v17
	v_lshlrev_b32_e32 v36, 16, v21
	s_waitcnt vmcnt(1)
	v_max3_f32 v16, v28, v30, v32
	v_sub_f32_e32 v20, v28, v16
	v_sub_f32_e32 v28, v30, v16
	v_sub_f32_e32 v16, v32, v16
	v_exp_f32_e32 v20, v20
	v_mov_b32_e32 v30, v33
	v_exp_f32_e32 v33, v28
	v_exp_f32_e32 v32, v16
	v_fma_f32 v16, v20, v38, 0
	v_fma_f32 v38, v20, v39, 0
	v_fma_f32 v39, v20, v40, 0
	v_fma_f32 v40, v20, v41, 0
	v_fma_f32 v41, v20, v42, 0
	v_fma_f32 v42, v20, v43, 0
	v_fma_f32 v43, v20, v44, 0
	v_fma_f32 v44, v20, v45, 0
	v_fma_f32 v20, v29, v20, 0
	v_pk_mul_f32 v[28:29], v[30:31], v[32:33]
	v_mov_b32_e32 v30, v33
	v_mov_b32_e32 v31, v32
	v_add_f32_e32 v20, v29, v20
	v_pk_mul_f32 v[10:11], v[30:31], v[10:11]
	v_pk_mul_f32 v[32:33], v[30:31], v[34:35]
	v_pk_mul_f32 v[34:35], v[30:31], v[36:37]
	v_pk_mul_f32 v[12:13], v[30:31], v[12:13]
	v_add_f32_e32 v10, v16, v10
	v_add_f32_e32 v29, v42, v32
	v_add_f32_e32 v32, v43, v34
	v_add_f32_e32 v34, v28, v20
	v_add_f32_e32 v12, v38, v12
	v_add_f32_e32 v10, v10, v11
	v_div_scale_f32 v11, s[20:21], v34, v34, 1.0
	v_add_f32_e32 v12, v12, v13
	v_rcp_f32_e32 v13, v11
	v_lshlrev_b32_e32 v27, 16, v15
	v_and_b32_e32 v15, 0xffff0000, v15
	v_pk_mul_f32 v[26:27], v[30:31], v[26:27]
	v_pk_mul_f32 v[14:15], v[30:31], v[14:15]
	v_add_f32_e32 v16, v39, v26
	v_add_f32_e32 v26, v40, v14
	v_add_f32_e32 v14, v16, v27
	v_add_f32_e32 v16, v26, v15
	v_fma_f32 v15, -v11, v13, 1.0
	v_pk_mul_f32 v[18:19], v[30:31], v[18:19]
	v_fmac_f32_e32 v13, v15, v13
	v_div_scale_f32 v15, vcc, 1.0, v34, 1.0
	v_add_f32_e32 v18, v41, v18
	v_add_f32_e32 v20, v29, v33
	v_and_b32_e32 v29, 0xffff0000, v17
	v_mul_f32_e32 v17, v15, v13
	v_add_f32_e32 v18, v18, v19
	v_fma_f32 v19, -v11, v17, v15
	v_fmac_f32_e32 v17, v19, v13
	v_fma_f32 v15, -v11, v17, v15
	s_waitcnt vmcnt(0)
	v_lshlrev_b32_e32 v11, 16, v22
	v_mul_f32_e32 v19, 0xbfb8aa3b, v11
	v_exp_f32_e32 v19, v19
	v_div_fmas_f32 v15, v15, v13, v17
	v_and_b32_e32 v13, 0xffff0000, v22
	v_add_f32_e32 v26, v32, v35
	v_add_f32_e32 v17, 1.0, v19
	v_rcp_f32_e32 v33, v17
	v_mul_f32_e32 v17, 0xbfb8aa3b, v13
	v_exp_f32_e32 v17, v17
	v_div_fixup_f32 v32, v15, v34, 1.0
	v_lshlrev_b32_e32 v15, 16, v23
	v_pk_mul_f32 v[10:11], v[32:33], v[10:11]
	v_add_f32_e32 v17, 1.0, v17
	v_rcp_f32_e32 v33, v17
	v_mul_f32_e32 v17, 0xbfb8aa3b, v15
	v_exp_f32_e32 v19, v17
	v_and_b32_e32 v17, 0xffff0000, v23
	v_pk_mul_f32 v[12:13], v[32:33], v[12:13]
	v_and_b32_e32 v28, 0xffff0000, v21
	v_add_f32_e32 v19, 1.0, v19
	v_rcp_f32_e32 v33, v19
	v_mul_f32_e32 v19, 0xbfb8aa3b, v17
	v_exp_f32_e32 v21, v19
	v_lshlrev_b32_e32 v19, 16, v24
	v_pk_mul_f32 v[14:15], v[32:33], v[14:15]
	v_lshlrev_b32_e32 v27, 16, v25
	v_add_f32_e32 v21, 1.0, v21
	v_rcp_f32_e32 v33, v21
	v_mul_f32_e32 v21, 0xbfb8aa3b, v19
	v_exp_f32_e32 v23, v21
	v_and_b32_e32 v21, 0xffff0000, v24
	v_pk_mul_f32 v[16:17], v[32:33], v[16:17]
	v_pk_mul_f32 v[28:29], v[30:31], v[28:29]
	v_add_f32_e32 v23, 1.0, v23
	v_rcp_f32_e32 v33, v23
	v_mul_f32_e32 v23, 0xbfb8aa3b, v21
	v_exp_f32_e32 v24, v23
	v_add_f32_e32 v22, v44, v28
	v_pk_mul_f32 v[18:19], v[32:33], v[18:19]
	v_and_b32_e32 v23, 0xffff0000, v25
	v_add_f32_e32 v24, 1.0, v24
	v_rcp_f32_e32 v33, v24
	v_mul_f32_e32 v24, 0xbfb8aa3b, v27
	v_exp_f32_e32 v24, v24
	v_mul_f32_e32 v28, v12, v13
	v_mul_f32_e32 v25, v10, v11
	v_pk_mul_f32 v[10:11], v[32:33], v[20:21]
	v_add_f32_e32 v12, 1.0, v24
	v_rcp_f32_e32 v33, v12
	v_mul_f32_e32 v12, 0xbfb8aa3b, v23
	v_exp_f32_e32 v20, v12
	v_mul_f32_e32 v14, v14, v15
	v_mul_f32_e32 v15, v16, v17
	v_pk_mul_f32 v[12:13], v[32:33], v[26:27]
	v_add_f32_e32 v16, 1.0, v20
	v_rcp_f32_e32 v33, v16
	v_add_f32_e32 v22, v22, v29
	v_mul_f32_e32 v17, v10, v11
	v_mul_f32_e32 v16, v18, v19
	v_pk_mul_f32 v[10:11], v[32:33], v[22:23]
	v_mul_f32_e32 v13, v12, v13
	v_mul_f32_e32 v18, v10, v11
	v_cvt_pk_bf16_f32 v10, v25, v28
	v_cvt_pk_bf16_f32 v11, v14, v15
	v_lshlrev_b64 v[14:15], 13, v[0:1]
	v_add_u32_e32 v0, s8, v0
	v_cmp_lt_i32_e32 vcc, s12, v0
	v_lshl_add_u64 v[14:15], v[8:9], 0, v[14:15]
	s_or_b64 s[6:7], vcc, s[6:7]
	v_cvt_pk_bf16_f32 v12, v16, v17
	v_cvt_pk_bf16_f32 v13, v13, v18
	global_store_dwordx4 v[14:15], v[10:13], off sc1
	s_andn2_b64 exec, exec, s[6:7]
	s_cbranch_execnz .LBB0_389
